# v_k3 + V-transpose loads hoisted + attention-epilogue gate loads hoisted (8 loads in flight, counted waits)
# baseline (speedup 1.0000x reference)
; #define MFMA32(a, b, c) __builtin_amdgcn_mfma_f32_32x32x16_bf16((a), (b), (c), 0, 0, 0)
; template <int TYPE>
; DI void attn_item(const Params& p, int l, int bb, int head, int qb, char* smem) {
;     ...
;         const float mcur = mrun[mp];
; #pragma unroll
;         for (int kb = 0; kb < 2; kb++)
; #pragma unroll
;           for (int i = 0; i < 16; i++) { float e = __builtin_amdgcn_exp2f(s[kb][i] - mcur); s[kb][i] = e; psum += e; }
;       } else {
;         if (__builtin_amdgcn_ballot_w64(mx > 0.f) != 0ull) {
;           float delta = fmaxf(mx, 0.f);
;           float alpha = __builtin_amdgcn_exp2f(-delta);
;           mrun[mp] += delta;
;           lrun[mp] *= alpha;
; #pragma unroll
;           for (int d = 0; d < 2; d++)
; #pragma unroll
;             for (int i = 0; i < 16; i++) O[mp][d][i] *= alpha;
; #pragma unroll
;           for (int kb = 0; kb < 2; kb++)
; #pragma unroll
;             for (int i = 0; i < 16; i++) s[kb][i] -= delta;
;           const float nmv = -mrun[mp];
; #pragma unroll
;           for (int i = 0; i < 16; i++) nm[i] = nmv;
;         }
; #pragma unroll
;         for (int kb = 0; kb < 2; kb++)
; #pragma unroll
;           for (int i = 0; i < 16; i++) { float e = __builtin_amdgcn_exp2f(s[kb][i]); s[kb][i] = e; psum += e; }
;       }
;       lrun[mp] += psum;
; #pragma unroll
;       for (int kb = 0; kb < 2; kb++)
; #pragma unroll
;         for (int s2 = 0; s2 < 2; s2++) {
;           unsigned pw[4];
; #pragma unroll
;           for (int e = 0; e < 4; e++) pw[e] = pack2(s[kb][8 * s2 + 2 * e], s[kb][8 * s2 + 2 * e + 1]);
;           u32x4 pu = u32x4{pw[0], pw[1], pw[2], pw[3]};
;           bf16x8 pf = __builtin_bit_cast(bf16x8, pu);
; #pragma unroll
;           for (int d = 0; d < 2; d++) {
;             const u16* vp = sV + (d * 32 + r) * 72 + kb * 32 + s2 * 16 + 4 * h;
;             s16x4 vlo = *(const s16x4*)vp, vhi = *(const s16x4*)(vp + 8);
;             bf16x8 vf = __builtin_shufflevector(vlo, vhi, 0, 1, 2, 3, 4, 5, 6, 7);
;             O[mp][d] = MFMA32(vf, pf, O[mp][d]);
;           }
;         }
;     }
;     __syncthreads();
.LBB0_377:
	v_sub_f32_e32 v80, v80, v169
	v_exp_f32_e32 v80, v80
	v_sub_f32_e32 v81, v81, v169
	v_exp_f32_e32 v81, v81
	v_sub_f32_e32 v82, v82, v169
	v_exp_f32_e32 v82, v82
	v_sub_f32_e32 v83, v83, v169
	v_exp_f32_e32 v83, v83
	v_sub_f32_e32 v84, v84, v169
	v_add_f32_e32 v97, 0, v80
	v_exp_f32_e32 v84, v84
	v_sub_f32_e32 v85, v85, v169
	v_add_f32_e32 v97, v81, v97
	v_exp_f32_e32 v85, v85
	v_sub_f32_e32 v86, v86, v169
	v_add_f32_e32 v97, v82, v97
	v_exp_f32_e32 v86, v86
	v_sub_f32_e32 v87, v87, v169
	v_add_f32_e32 v97, v83, v97
	v_exp_f32_e32 v87, v87
	v_sub_f32_e32 v88, v88, v169
	v_add_f32_e32 v97, v84, v97
	v_exp_f32_e32 v88, v88
	v_sub_f32_e32 v89, v89, v169
	v_add_f32_e32 v97, v85, v97
	v_exp_f32_e32 v89, v89
	v_sub_f32_e32 v90, v90, v169
	v_add_f32_e32 v97, v86, v97
	v_exp_f32_e32 v90, v90
	v_sub_f32_e32 v91, v91, v169
	v_add_f32_e32 v97, v87, v97
	v_exp_f32_e32 v91, v91
	v_sub_f32_e32 v92, v92, v169
	v_add_f32_e32 v97, v88, v97
	v_exp_f32_e32 v92, v92
	v_sub_f32_e32 v93, v93, v169
	v_add_f32_e32 v97, v89, v97
	v_exp_f32_e32 v93, v93
	v_sub_f32_e32 v94, v94, v169
	v_add_f32_e32 v97, v90, v97
	v_exp_f32_e32 v94, v94
	v_sub_f32_e32 v95, v95, v169
	v_add_f32_e32 v97, v91, v97
	v_exp_f32_e32 v95, v95
	v_sub_f32_e32 v64, v64, v169
	v_add_f32_e32 v97, v92, v97
	v_exp_f32_e32 v98, v64
	v_add_f32_e32 v97, v93, v97
	v_add_f32_e32 v97, v94, v97
	v_add_f32_e32 v97, v95, v97
	v_sub_f32_e32 v65, v65, v169
	v_add_f32_e32 v64, v98, v97
	v_exp_f32_e32 v97, v65
	v_sub_f32_e32 v65, v66, v169
	v_exp_f32_e32 v99, v65
	v_sub_f32_e32 v65, v67, v169
	v_exp_f32_e32 v100, v65
	v_sub_f32_e32 v65, v68, v169
	v_exp_f32_e32 v68, v65
	v_sub_f32_e32 v65, v69, v169
	v_add_f32_e32 v64, v97, v64
	v_exp_f32_e32 v69, v65
	v_sub_f32_e32 v65, v70, v169
	v_add_f32_e32 v64, v99, v64
	v_exp_f32_e32 v70, v65
	v_sub_f32_e32 v65, v71, v169
	v_add_f32_e32 v64, v100, v64
	v_exp_f32_e32 v71, v65
	v_sub_f32_e32 v65, v72, v169
	v_add_f32_e32 v64, v68, v64
	v_exp_f32_e32 v72, v65
	v_sub_f32_e32 v65, v73, v169
	v_add_f32_e32 v64, v69, v64
	v_exp_f32_e32 v73, v65
	v_sub_f32_e32 v65, v74, v169
	v_add_f32_e32 v64, v70, v64
	v_exp_f32_e32 v74, v65
	v_sub_f32_e32 v65, v75, v169
	v_add_f32_e32 v64, v71, v64
	v_exp_f32_e32 v75, v65
	v_sub_f32_e32 v65, v76, v169
	v_add_f32_e32 v96, 0, v136
	v_add_f32_e32 v64, v72, v64
	v_exp_f32_e32 v76, v65
	v_sub_f32_e32 v65, v77, v169
	v_add_f32_e32 v96, v137, v96
	v_add_f32_e32 v64, v73, v64
	v_exp_f32_e32 v77, v65
	v_sub_f32_e32 v65, v78, v169
	v_add_f32_e32 v96, v138, v96
	v_add_f32_e32 v64, v74, v64
	v_exp_f32_e32 v78, v65
	v_sub_f32_e32 v65, v79, v169
	v_add_f32_e32 v96, v139, v96
	v_add_f32_e32 v64, v75, v64
	v_exp_f32_e32 v79, v65
	v_add_f32_e32 v96, v140, v96
	v_add_f32_e32 v64, v76, v64
	v_add_f32_e32 v96, v141, v96
	v_add_f32_e32 v64, v77, v64
	v_add_f32_e32 v96, v142, v96
	v_add_f32_e32 v64, v78, v64
	v_add_f32_e32 v96, v143, v96
	v_add_f32_e32 v64, v79, v64
	v_add_f32_e32 v96, v144, v96
	v_add_f32_e32 v101, v168, v64
	v_cvt_pk_bf16_f32 v64, v80, v81
	v_cvt_pk_bf16_f32 v65, v82, v83
	v_cvt_pk_bf16_f32 v66, v84, v85
	v_cvt_pk_bf16_f32 v67, v86, v87
	v_add_f32_e32 v96, v145, v96
	v_add_f32_e32 v96, v146, v96
	v_mfma_f32_32x32x16_bf16 v[48:63], v[108:111], v[64:67], v[48:63]
	v_add_f32_e32 v96, v147, v96
	v_add_f32_e32 v96, v148, v96
	v_add_f32_e32 v96, v149, v96
	v_add_f32_e32 v96, v150, v96
	v_add_f32_e32 v96, v151, v96
	v_add_f32_e32 v96, v152, v96
	v_add_f32_e32 v96, v153, v96
	v_mfma_f32_32x32x16_bf16 v[16:31], v[112:115], v[64:67], v[16:31]
	v_cvt_pk_bf16_f32 v64, v88, v89
	v_cvt_pk_bf16_f32 v65, v90, v91
	v_cvt_pk_bf16_f32 v66, v92, v93
	v_cvt_pk_bf16_f32 v67, v94, v95
	v_add_f32_e32 v96, v154, v96
	v_add_f32_e32 v96, v155, v96
	v_add_f32_e32 v96, v156, v96
	v_mfma_f32_32x32x16_bf16 v[48:63], v[104:107], v[64:67], v[48:63]
	v_add_f32_e32 v96, v157, v96
	v_add_f32_e32 v96, v158, v96
	v_add_f32_e32 v96, v159, v96
	v_add_f32_e32 v96, v160, v96
	v_add_f32_e32 v96, v161, v96
	v_add_f32_e32 v96, v162, v96
	v_add_f32_e32 v96, v163, v96
	v_mfma_f32_32x32x16_bf16 v[16:31], v[116:119], v[64:67], v[16:31]
	v_cvt_pk_bf16_f32 v64, v98, v97
	v_cvt_pk_bf16_f32 v65, v99, v100
	v_cvt_pk_bf16_f32 v66, v68, v69
	v_cvt_pk_bf16_f32 v67, v70, v71
	v_add_f32_e32 v96, v164, v96
	v_add_f32_e32 v96, v165, v96
	v_add_f32_e32 v96, v166, v96
	v_mfma_f32_32x32x16_bf16 v[48:63], v[120:123], v[64:67], v[48:63]
	v_add_f32_e32 v96, v167, v96
	v_add_f32_e32 v96, v170, v96
	s_barrier
; DI int otid() { int t; asm volatile("v_mov_b32 %0, %1" : "=v"(t) : "v"((int)threadIdx.x)); return t; }
; DI float lo_bf(unsigned w) { return __uint_as_float(w << 16); }
; DI float hi_bf(unsigned w) { return __uint_as_float(w & 0xffff0000u); }
; DI float xsum32(float x) { auto r = __builtin_amdgcn_permlane32_swap(__float_as_uint(x), __float_as_uint(x), false, false); return __uint_as_float(r[0]) + __uint_as_float(r[1]); }
; template <int TYPE>
; DI void attn_item(const Params& p, int l, int bb, int head, int qb, char* smem) {
;     ...
;   float inv[NMAP];
; #pragma unroll
;   for (int mp = 0; mp < NMAP; mp++) { float lt = xsum32(lrun[mp]); inv[mp] = 1.f / lt; }
;   const int tid2 = otid();
;   const int r2 = tid2 & 31, h2 = (tid2 >> 5) & 1, wv2 = tid2 >> 6;
;   const int t = qb * 128 + wv2 * 32 + r2;
;   const long mh = (long)bb * T + t;
;   const int gcol = (TYPE == 0) ? 0 : (TYPE == 1 ? 512 : 768);
;   const int ocol = (TYPE == 0) ? 0 : (TYPE == 1 ? 512 : 768);
;   float val[2][16];
;   if (TYPE == 2) {
;     float lam = p.lam[l], li = p.lam[2 + l];
;     float ss = 0.f;
; #pragma unroll
;     for (int d = 0; d < 2; d++)
; #pragma unroll
;       for (int i = 0; i < 16; i++) { float x = O[0][d][i] * inv[0] - lam * O[NMAP - 1][d][i] * inv[NMAP - 1]; val[d][i] = x; ss += x * x; }
;     ss = xsum32(ss);
;     float rs = rsqrtf(ss * (1.f / 64.f) + 1e-5f) * (1.f - li);
;     const float* sg = p.in[24] + l * 64;
; #pragma unroll
;     for (int d = 0; d < 2; d++)
; #pragma unroll
;       for (int i = 0; i < 16; i++) { int dv = d * 32 + (i & 3) + 8 * (i >> 2) + 4 * h2; val[d][i] *= rs * sg[dv]; }
;   } else {
; #pragma unroll
;     for (int d = 0; d < 2; d++)
; #pragma unroll
;       for (int i = 0; i < 16; i++) val[d][i] = O[0][d][i] * inv[0];
;   }
; #pragma unroll
;   for (int d = 0; d < 2; d++)
; #pragma unroll
;     for (int g = 0; g < 4; g++) {
;       int dv0 = d * 32 + 8 * g + 4 * h2;
;       u32x2 gw = *(const u32x2*)(p.Gs + mh * 1024 + gcol + head * 64 + dv0);
;       float g0 = lo_bf(gw.x), g1 = hi_bf(gw.x), g2 = lo_bf(gw.y), g3 = hi_bf(gw.y);
	s_mul_i32 s26, s37, 0x1100
	v_readlane_b32 s40, v254, 18
	v_mfma_f32_32x32x16_bf16 v[16:31], v[124:127], v[64:67], v[16:31]
	v_cvt_pk_bf16_f32 v64, v72, v73
	v_cvt_pk_bf16_f32 v65, v74, v75
	v_cvt_pk_bf16_f32 v66, v76, v77
	v_cvt_pk_bf16_f32 v67, v78, v79
	v_readlane_b32 s41, v254, 19
	v_readlane_b32 s42, v254, 20
	v_readlane_b32 s43, v254, 21
	v_mfma_f32_32x32x16_bf16 v[48:63], v[128:131], v[64:67], v[48:63]
	v_mfma_f32_32x32x16_bf16 v[16:31], v[132:135], v[64:67], v[16:31]
	v_mov_b32_e32 v64, v96
	s_nop 1
	v_permlane32_swap_b32_e32 v96, v64
	v_add_f32_e32 v64, v96, v64
	v_div_scale_f32 v65, s[12:13], v64, v64, 1.0
	v_rcp_f32_e32 v66, v65
	s_nop 0
	v_fma_f32 v67, -v65, v66, 1.0
	v_fmac_f32_e32 v66, v67, v66
	v_div_scale_f32 v67, vcc, 1.0, v64, 1.0
	v_mul_f32_e32 v68, v67, v66
	v_fma_f32 v69, -v65, v68, v67
	v_fmac_f32_e32 v68, v69, v66
	v_fma_f32 v65, -v65, v68, v67
	v_div_fmas_f32 v65, v65, v66, v68
	v_div_fixup_f32 v70, v65, v64, 1.0
	v_mov_b32_e32 v64, v101
	s_nop 1
	v_permlane32_swap_b32_e32 v101, v64
	v_add_f32_e32 v64, v101, v64
	v_div_scale_f32 v65, s[12:13], v64, v64, 1.0
	v_rcp_f32_e32 v66, v65
	v_readlane_b32 s12, v255, 40
	v_readlane_b32 s13, v255, 41
	v_fma_f32 v67, -v65, v66, 1.0
	v_fmac_f32_e32 v66, v67, v66
	v_div_scale_f32 v67, vcc, 1.0, v64, 1.0
	v_mul_f32_e32 v68, v67, v66
	v_fma_f32 v69, -v65, v68, v67
	v_fmac_f32_e32 v68, v69, v66
	v_fma_f32 v65, -v65, v68, v67
	v_div_fmas_f32 v65, v65, v66, v68
	v_div_fixup_f32 v72, v65, v64, 1.0
	v_mov_b32 v66, v198
	global_load_dword v74, v177, s[12:13]
	global_load_dword v67, v177, s[12:13] offset:8
	v_ashrrev_i32_e32 v64, 1, v66
	v_and_b32_e32 v64, 0xffffffe0, v64
	v_add_u32_e32 v64, s38, v64
	v_and_or_b32 v64, v66, 31, v64
	v_ashrrev_i32_e32 v65, 31, v64
	v_lshl_add_u64 v[64:65], v[64:65], 0, s[26:27]
	v_lshrrev_b32_e32 v66, 3, v66
	v_lshlrev_b64 v[76:77], 11, v[64:65]
	v_and_b32_e32 v66, 4, v66
	v_lshl_add_u64 v[64:65], s[94:95], 0, v[76:77]
	s_lshl_b32 s26, s36, 7
	v_lshl_add_u64 v[64:65], v[64:65], 0, s[26:27]
	v_lshlrev_b32_e32 v176, 1, v66
	v_lshl_add_u64 v[68:69], v[64:65], 0, v[176:177]
	global_load_dwordx2 v[80:81], v[68:69], off offset:1536
	global_load_dwordx2 v[236:237], v[68:69], off offset:1552
	global_load_dwordx2 v[238:239], v[68:69], off offset:1568
	global_load_dwordx2 v[240:241], v[68:69], off offset:1584
	global_load_dwordx2 v[242:243], v[68:69], off offset:1600
	global_load_dwordx2 v[244:245], v[68:69], off offset:1616
	global_load_dwordx2 v[246:247], v[68:69], off offset:1632
	global_load_dwordx2 v[248:249], v[68:69], off offset:1648
	v_lshlrev_b32_e32 v73, 2, v66
	v_readlane_b32 s12, v255, 42
	v_readlane_b32 s13, v255, 43
	s_waitcnt vmcnt(9)
	v_pk_mul_f32 v[50:51], v[50:51], v[74:75] op_sel_hi:[1, 0]
	s_waitcnt vmcnt(8)
	v_sub_f32_e32 v71, 1.0, v67
	v_pk_mul_f32 v[50:51], v[50:51], v[72:73] op_sel_hi:[1, 0]
	v_pk_mul_f32 v[54:55], v[54:55], v[74:75] op_sel_hi:[1, 0]
	v_pk_fma_f32 v[50:51], v[34:35], v[70:71], v[50:51] op_sel_hi:[1, 0, 1] neg_lo:[0, 0, 1] neg_hi:[0, 0, 1]
	v_pk_mul_f32 v[34:35], v[48:49], v[74:75] op_sel_hi:[1, 0]
	v_pk_mul_f32 v[54:55], v[54:55], v[72:73] op_sel_hi:[1, 0]
	v_pk_mul_f32 v[34:35], v[34:35], v[72:73] op_sel_hi:[1, 0]
	v_pk_mul_f32 v[18:19], v[18:19], v[74:75] op_sel_hi:[1, 0]
	v_pk_fma_f32 v[78:79], v[32:33], v[70:71], v[34:35] op_sel_hi:[1, 0, 1] neg_lo:[0, 0, 1] neg_hi:[0, 0, 1]
	v_pk_mul_f32 v[18:19], v[18:19], v[72:73] op_sel_hi:[1, 0]
	v_mul_f32_e32 v32, v79, v79
	v_pk_fma_f32 v[32:33], v[78:79], v[78:79], v[32:33] op_sel_hi:[1, 1, 0]
	global_load_dwordx4 v[64:67], v73, s[12:13]
	v_pk_fma_f32 v[32:33], v[50:51], v[50:51], v[32:33]
	s_waitcnt vmcnt(8)
	v_lshlrev_b32_e32 v34, 16, v80
	v_and_b32_e32 v35, 0xffff0000, v80
	v_mul_f32_e32 v48, 0xbfb8aa3b, v34
	v_mul_f32_e32 v49, 0xbfb8aa3b, v35
	v_exp_f32_e32 v48, v48
	v_exp_f32_e32 v49, v49
	v_lshlrev_b32_e32 v82, 16, v81
	v_and_b32_e32 v83, 0xffff0000, v81
	v_add_f32_e32 v48, 1.0, v48
	v_add_f32_e32 v49, 1.0, v49
	v_rcp_f32_e32 v48, v48
	v_rcp_f32_e32 v49, v49
	s_nop 0
	v_pk_mul_f32 v[34:35], v[48:49], v[34:35]
	v_mul_f32_e32 v48, v51, v51
	v_pk_add_f32 v[84:85], v[48:49], v[32:33] op_sel_hi:[0, 1]
	v_mul_f32_e32 v32, 0xbfb8aa3b, v82
	v_mul_f32_e32 v33, 0xbfb8aa3b, v83
	v_exp_f32_e32 v32, v32
	v_exp_f32_e32 v33, v33
	v_add_f32_e32 v32, 1.0, v32
	v_add_f32_e32 v33, 1.0, v33
	v_rcp_f32_e32 v32, v32
	v_rcp_f32_e32 v33, v33
	s_nop 0
	v_pk_mul_f32 v[48:49], v[32:33], v[82:83]
	v_lshl_add_u64 v[32:33], s[40:41], 0, v[76:77]
	v_pk_fma_f32 v[76:77], v[38:39], v[70:71], v[54:55] op_sel_hi:[1, 0, 1] neg_lo:[0, 0, 1] neg_hi:[0, 0, 1]
	v_pk_mul_f32 v[38:39], v[52:53], v[74:75] op_sel_hi:[1, 0]
	global_load_dwordx4 v[80:83], v73, s[12:13] offset:32
	v_pk_mul_f32 v[38:39], v[38:39], v[72:73] op_sel_hi:[1, 0]
	v_lshl_add_u64 v[32:33], v[32:33], 0, s[26:27]
	v_pk_fma_f32 v[86:87], v[36:37], v[70:71], v[38:39] op_sel_hi:[1, 0, 1] neg_lo:[0, 0, 1] neg_hi:[0, 0, 1]
	v_lshl_add_u64 v[32:33], v[32:33], 0, v[176:177]
	v_pk_fma_f32 v[36:37], v[86:87], v[86:87], v[84:85]
	v_mul_f32_e32 v38, v87, v87
	v_pk_add_f32 v[36:37], v[38:39], v[36:37] op_sel_hi:[0, 1]
	v_pk_fma_f32 v[36:37], v[76:77], v[76:77], v[36:37]
	v_mul_f32_e32 v38, v77, v77
	v_pk_add_f32 v[52:53], v[38:39], v[36:37] op_sel_hi:[0, 1]
	v_pk_mul_f32 v[36:37], v[58:59], v[74:75] op_sel_hi:[1, 0]
	v_pk_fma_f32 v[84:85], v[2:3], v[70:71], v[18:19] op_sel_hi:[1, 0, 1] neg_lo:[0, 0, 1] neg_hi:[0, 0, 1]
	v_pk_mul_f32 v[36:37], v[36:37], v[72:73] op_sel_hi:[1, 0]
	v_pk_mul_f32 v[2:3], v[16:17], v[74:75] op_sel_hi:[1, 0]
	v_pk_fma_f32 v[58:59], v[42:43], v[70:71], v[36:37] op_sel_hi:[1, 0, 1] neg_lo:[0, 0, 1] neg_hi:[0, 0, 1]
; DI float xsum32(float x) { auto r = __builtin_amdgcn_permlane32_swap(__float_as_uint(x), __float_as_uint(x), false, false); return __uint_as_float(r[0]) + __uint_as_float(r[1]); }
; template <int TYPE>
; DI void attn_item(const Params& p, int l, int bb, int head, int qb, char* smem) {
;     ...
;     for (int d = 0; d < 2; d++)
; #pragma unroll
;       for (int i = 0; i < 16; i++) { float x = O[0][d][i] * inv[0] - lam * O[NMAP - 1][d][i] * inv[NMAP - 1]; val[d][i] = x; ss += x * x; }
;     ss = xsum32(ss);
;     float rs = rsqrtf(ss * (1.f / 64.f) + 1e-5f) * (1.f - li);
;     const float* sg = p.in[24] + l * 64;
; #pragma unroll
;     for (int d = 0; d < 2; d++)
; #pragma unroll
;       for (int i = 0; i < 16; i++) { int dv = d * 32 + (i & 3) + 8 * (i >> 2) + 4 * h2; val[d][i] *= rs * sg[dv]; }
	v_pk_mul_f32 v[42:43], v[56:57], v[74:75] op_sel_hi:[1, 0]
	v_pk_mul_f32 v[2:3], v[2:3], v[72:73] op_sel_hi:[1, 0]
	v_pk_mul_f32 v[42:43], v[42:43], v[72:73] op_sel_hi:[1, 0]
	v_pk_fma_f32 v[88:89], v[0:1], v[70:71], v[2:3] op_sel_hi:[1, 0, 1] neg_lo:[0, 0, 1] neg_hi:[0, 0, 1]
	v_pk_fma_f32 v[56:57], v[40:41], v[70:71], v[42:43] op_sel_hi:[1, 0, 1] neg_lo:[0, 0, 1] neg_hi:[0, 0, 1]
	v_mul_f32_e32 v2, v89, v89
	v_pk_fma_f32 v[40:41], v[56:57], v[56:57], v[52:53]
	v_mul_f32_e32 v42, v57, v57
	v_pk_add_f32 v[40:41], v[42:43], v[40:41] op_sel_hi:[0, 1]
	v_pk_fma_f32 v[40:41], v[58:59], v[58:59], v[40:41]
	v_mul_f32_e32 v42, v59, v59
	v_pk_add_f32 v[52:53], v[42:43], v[40:41] op_sel_hi:[0, 1]
	v_pk_mul_f32 v[40:41], v[62:63], v[74:75] op_sel_hi:[1, 0]
	global_load_dwordx4 v[36:39], v73, s[12:13] offset:64
	v_pk_mul_f32 v[40:41], v[40:41], v[72:73] op_sel_hi:[1, 0]
	v_pk_mul_f32 v[18:19], v[20:21], v[74:75] op_sel_hi:[1, 0]
	v_pk_fma_f32 v[62:63], v[46:47], v[70:71], v[40:41] op_sel_hi:[1, 0, 1] neg_lo:[0, 0, 1] neg_hi:[0, 0, 1]
	v_pk_mul_f32 v[46:47], v[60:61], v[74:75] op_sel_hi:[1, 0]
	v_pk_mul_f32 v[18:19], v[18:19], v[72:73] op_sel_hi:[1, 0]
	v_pk_mul_f32 v[46:47], v[46:47], v[72:73] op_sel_hi:[1, 0]
	global_load_dwordx4 v[40:43], v73, s[12:13] offset:96
	v_pk_fma_f32 v[60:61], v[44:45], v[70:71], v[46:47] op_sel_hi:[1, 0, 1] neg_lo:[0, 0, 1] neg_hi:[0, 0, 1]
	v_pk_fma_f32 v[4:5], v[4:5], v[70:71], v[18:19] op_sel_hi:[1, 0, 1] neg_lo:[0, 0, 1] neg_hi:[0, 0, 1]
	v_pk_fma_f32 v[44:45], v[60:61], v[60:61], v[52:53]
	v_mul_f32_e32 v46, v61, v61
	v_pk_add_f32 v[44:45], v[46:47], v[44:45] op_sel_hi:[0, 1]
	v_pk_fma_f32 v[44:45], v[62:63], v[62:63], v[44:45]
	v_mul_f32_e32 v46, v63, v63
	v_pk_add_f32 v[52:53], v[46:47], v[44:45] op_sel_hi:[0, 1]
	v_pk_fma_f32 v[0:1], v[88:89], v[88:89], v[52:53]
	v_mul_f32_e32 v18, v5, v5
	v_pk_add_f32 v[0:1], v[2:3], v[0:1] op_sel_hi:[0, 1]
	v_pk_fma_f32 v[0:1], v[84:85], v[84:85], v[0:1]
	v_mul_f32_e32 v2, v85, v85
	v_pk_add_f32 v[16:17], v[2:3], v[0:1] op_sel_hi:[0, 1]
	v_pk_mul_f32 v[0:1], v[22:23], v[74:75] op_sel_hi:[1, 0]
	v_pk_fma_f32 v[16:17], v[4:5], v[4:5], v[16:17]
	v_pk_mul_f32 v[0:1], v[0:1], v[72:73] op_sel_hi:[1, 0]
	global_load_dwordx4 v[44:47], v73, s[12:13] offset:128
	v_pk_fma_f32 v[6:7], v[6:7], v[70:71], v[0:1] op_sel_hi:[1, 0, 1] neg_lo:[0, 0, 1] neg_hi:[0, 0, 1]
	global_load_dwordx4 v[0:3], v73, s[12:13] offset:160
	v_pk_add_f32 v[16:17], v[18:19], v[16:17] op_sel_hi:[0, 1]
	v_pk_fma_f32 v[16:17], v[6:7], v[6:7], v[16:17]
	v_mul_f32_e32 v18, v7, v7
	v_pk_add_f32 v[16:17], v[18:19], v[16:17] op_sel_hi:[0, 1]
	v_pk_mul_f32 v[18:19], v[26:27], v[74:75] op_sel_hi:[1, 0]
	global_load_dwordx4 v[52:55], v73, s[12:13] offset:192
	v_pk_mul_f32 v[18:19], v[18:19], v[72:73] op_sel_hi:[1, 0]
	s_nop 0
	v_pk_fma_f32 v[90:91], v[10:11], v[70:71], v[18:19] op_sel_hi:[1, 0, 1] neg_lo:[0, 0, 1] neg_hi:[0, 0, 1]
	v_pk_mul_f32 v[10:11], v[24:25], v[74:75] op_sel_hi:[1, 0]
	global_load_dwordx4 v[24:27], v73, s[12:13] offset:224
	v_pk_mul_f32 v[10:11], v[10:11], v[72:73] op_sel_hi:[1, 0]
	s_mov_b32 s12, 0x800000
	v_pk_fma_f32 v[92:93], v[8:9], v[70:71], v[10:11] op_sel_hi:[1, 0, 1] neg_lo:[0, 0, 1] neg_hi:[0, 0, 1]
	s_nop 0
	v_pk_fma_f32 v[8:9], v[92:93], v[92:93], v[16:17]
	v_mul_f32_e32 v10, v93, v93
	v_pk_add_f32 v[8:9], v[10:11], v[8:9] op_sel_hi:[0, 1]
	v_pk_fma_f32 v[8:9], v[90:91], v[90:91], v[8:9]
	v_mul_f32_e32 v10, v91, v91
	v_pk_add_f32 v[8:9], v[10:11], v[8:9] op_sel_hi:[0, 1]
	v_pk_mul_f32 v[10:11], v[30:31], v[74:75] op_sel_hi:[1, 0]
	s_nop 0
	v_pk_mul_f32 v[10:11], v[10:11], v[72:73] op_sel_hi:[1, 0]
	s_nop 0
	v_pk_fma_f32 v[30:31], v[14:15], v[70:71], v[10:11] op_sel_hi:[1, 0, 1] neg_lo:[0, 0, 1] neg_hi:[0, 0, 1]
	v_pk_mul_f32 v[10:11], v[28:29], v[74:75] op_sel_hi:[1, 0]
	s_nop 0
	v_pk_mul_f32 v[10:11], v[10:11], v[72:73] op_sel_hi:[1, 0]
	s_nop 0
	v_pk_fma_f32 v[28:29], v[12:13], v[70:71], v[10:11] op_sel_hi:[1, 0, 1] neg_lo:[0, 0, 1] neg_hi:[0, 0, 1]
	s_nop 0
	v_pk_fma_f32 v[8:9], v[28:29], v[28:29], v[8:9]
	v_mul_f32_e32 v10, v29, v29
	v_pk_add_f32 v[8:9], v[10:11], v[8:9] op_sel_hi:[0, 1]
	v_pk_fma_f32 v[8:9], v[30:31], v[30:31], v[8:9]
	v_mul_f32_e32 v10, v31, v31
	v_pk_add_f32 v[8:9], v[10:11], v[8:9] op_sel_hi:[0, 1]
	v_mov_b32_e32 v9, v8
	s_nop 1
	v_permlane32_swap_b32_e32 v8, v9
	v_add_f32_e32 v8, v8, v9
	v_fmamk_f32 v8, v8, 0x3c800000, v201
	v_cmp_gt_f32_e32 vcc, s12, v8
	v_mul_f32_e32 v9, 0x4b800000, v8
	s_mov_b64 s[12:13], 0
	v_cndmask_b32_e32 v8, v8, v9, vcc
	v_rsq_f32_e32 v8, v8
	s_nop 0
	v_mul_f32_e32 v9, 0x45800000, v8
	v_cndmask_b32_e32 v8, v8, v9, vcc
	v_mul_f32_e32 v70, v71, v8
	s_waitcnt vmcnt(7)
	v_pk_mul_f32 v[8:9], v[64:65], v[70:71] op_sel_hi:[1, 0]
	s_waitcnt vmcnt(2)
	v_pk_mul_f32 v[0:1], v[70:71], v[0:1] op_sel_hi:[0, 1]
	v_pk_mul_f32 v[64:65], v[78:79], v[8:9]
	v_pk_mul_f32 v[8:9], v[66:67], v[70:71] op_sel_hi:[1, 0]
	v_pk_mul_f32 v[10:11], v[4:5], v[0:1]
	v_pk_mul_f32 v[50:51], v[50:51], v[8:9]
	v_pk_mul_f32 v[8:9], v[80:81], v[70:71] op_sel_hi:[1, 0]
	v_pk_mul_f32 v[0:1], v[70:71], v[2:3] op_sel_hi:[0, 1]
	v_pk_mul_f32 v[66:67], v[86:87], v[8:9]
	v_pk_mul_f32 v[8:9], v[82:83], v[70:71] op_sel_hi:[1, 0]
	s_nop 0
	v_pk_mul_f32 v[72:73], v[76:77], v[8:9]
	v_pk_mul_f32 v[8:9], v[36:37], v[70:71] op_sel_hi:[1, 0]
	s_nop 0
	v_pk_mul_f32 v[22:23], v[56:57], v[8:9]
	v_pk_mul_f32 v[8:9], v[70:71], v[38:39] op_sel_hi:[0, 1]
	v_pk_mul_f32 v[20:21], v[58:59], v[8:9]
	v_pk_mul_f32 v[8:9], v[70:71], v[40:41] op_sel_hi:[0, 1]
	v_pk_mul_f32 v[18:19], v[60:61], v[8:9]
	v_pk_mul_f32 v[8:9], v[70:71], v[42:43] op_sel_hi:[0, 1]
	v_pk_mul_f32 v[16:17], v[62:63], v[8:9]
	v_pk_mul_f32 v[8:9], v[70:71], v[44:45] op_sel_hi:[0, 1]
	v_pk_mul_f32 v[14:15], v[88:89], v[8:9]
	v_pk_mul_f32 v[8:9], v[70:71], v[46:47] op_sel_hi:[0, 1]
	v_pk_mul_f32 v[12:13], v[84:85], v[8:9]
	v_pk_mul_f32 v[8:9], v[6:7], v[0:1]
	s_waitcnt vmcnt(1)
; DI float lo_bf(unsigned w) { return __uint_as_float(w << 16); }
; DI float hi_bf(unsigned w) { return __uint_as_float(w & 0xffff0000u); }
; DI float siluf_(float x) { return x * __builtin_amdgcn_rcpf(1.f + __builtin_amdgcn_exp2f(-1.4426950408889634f * x)); }
; template <int TYPE>
; DI void attn_item(const Params& p, int l, int bb, int head, int qb, char* smem) {
;     ...
; #pragma unroll
;   for (int d = 0; d < 2; d++)
; #pragma unroll
;     for (int g = 0; g < 4; g++) {
;       int dv0 = d * 32 + 8 * g + 4 * h2;
;       u32x2 gw = *(const u32x2*)(p.Gs + mh * 1024 + gcol + head * 64 + dv0);
;       float g0 = lo_bf(gw.x), g1 = hi_bf(gw.x), g2 = lo_bf(gw.y), g3 = hi_bf(gw.y);
;       u32x2 ow;
;       ow.x = pack2(val[d][4 * g] * siluf_(g0), val[d][4 * g + 1] * siluf_(g1));
;       ow.y = pack2(val[d][4 * g + 2] * siluf_(g2), val[d][4 * g + 3] * siluf_(g3));
;       *(u32x2*)(p.o + mh * DM + ocol + head * 64 + dv0) = ow;
;     }
	v_pk_mul_f32 v[0:1], v[70:71], v[52:53] op_sel_hi:[0, 1]
	v_pk_mul_f32 v[6:7], v[92:93], v[0:1]
	v_pk_mul_f32 v[0:1], v[70:71], v[54:55] op_sel_hi:[0, 1]
	v_pk_mul_f32 v[4:5], v[90:91], v[0:1]
	s_waitcnt vmcnt(0)
	v_pk_mul_f32 v[0:1], v[70:71], v[24:25] op_sel_hi:[0, 1]
	v_pk_mul_f32 v[2:3], v[28:29], v[0:1]
	v_pk_mul_f32 v[0:1], v[70:71], v[26:27] op_sel_hi:[0, 1]
	v_pk_mul_f32 v[24:25], v[64:65], v[34:35]
	v_pk_mul_f32 v[26:27], v[50:51], v[48:49]
	v_cvt_pk_bf16_f32 v24, v24, v25
	v_cvt_pk_bf16_f32 v25, v26, v27
	global_store_dwordx2 v[32:33], v[24:25], off offset:1536
	s_nop 0
	v_pk_mul_f32 v[0:1], v[30:31], v[0:1]
	s_waitcnt vmcnt(1)
	v_lshlrev_b32_e32 v26, 16, v236
	v_and_b32_e32 v27, 0xffff0000, v236
	v_mul_f32_e32 v28, 0xbfb8aa3b, v26
	v_mul_f32_e32 v29, 0xbfb8aa3b, v27
	v_exp_f32_e32 v28, v28
	v_exp_f32_e32 v29, v29
	v_lshlrev_b32_e32 v24, 16, v237
	v_and_b32_e32 v25, 0xffff0000, v237
	v_add_f32_e32 v28, 1.0, v28
	v_add_f32_e32 v29, 1.0, v29
	v_rcp_f32_e32 v28, v28
	v_rcp_f32_e32 v29, v29
	s_nop 0
	v_pk_mul_f32 v[26:27], v[28:29], v[26:27]
	s_nop 0
	v_pk_mul_f32 v[26:27], v[66:67], v[26:27]
	s_nop 0
	v_cvt_pk_bf16_f32 v26, v26, v27
	v_mul_f32_e32 v27, 0xbfb8aa3b, v24
	v_exp_f32_e32 v27, v27
	s_nop 0
	v_add_f32_e32 v27, 1.0, v27
	v_rcp_f32_e32 v28, v27
	v_mul_f32_e32 v27, 0xbfb8aa3b, v25
	v_exp_f32_e32 v27, v27
	s_nop 0
	v_add_f32_e32 v27, 1.0, v27
	v_rcp_f32_e32 v29, v27
	s_nop 0
	v_pk_mul_f32 v[24:25], v[28:29], v[24:25]
	s_nop 0
	v_pk_mul_f32 v[24:25], v[72:73], v[24:25]
	s_nop 0
	v_cvt_pk_bf16_f32 v27, v24, v25
	global_store_dwordx2 v[32:33], v[26:27], off offset:1552
	s_nop 0
	s_waitcnt vmcnt(2)
	v_lshlrev_b32_e32 v26, 16, v238
	v_and_b32_e32 v27, 0xffff0000, v238
	v_mul_f32_e32 v28, 0xbfb8aa3b, v26
	v_mul_f32_e32 v29, 0xbfb8aa3b, v27
	v_exp_f32_e32 v28, v28
	v_exp_f32_e32 v29, v29
	v_lshlrev_b32_e32 v24, 16, v239
	v_and_b32_e32 v25, 0xffff0000, v239
	v_add_f32_e32 v28, 1.0, v28
	v_add_f32_e32 v29, 1.0, v29
	v_rcp_f32_e32 v28, v28
	v_rcp_f32_e32 v29, v29
	s_nop 0
	v_pk_mul_f32 v[26:27], v[28:29], v[26:27]
	s_nop 0
	v_pk_mul_f32 v[22:23], v[22:23], v[26:27]
	s_nop 0
	v_cvt_pk_bf16_f32 v22, v22, v23
	v_mul_f32_e32 v23, 0xbfb8aa3b, v24
	v_exp_f32_e32 v23, v23
	s_nop 0
	v_add_f32_e32 v23, 1.0, v23
	v_rcp_f32_e32 v26, v23
	v_mul_f32_e32 v23, 0xbfb8aa3b, v25
	v_exp_f32_e32 v23, v23
	s_nop 0
	v_add_f32_e32 v23, 1.0, v23
	v_rcp_f32_e32 v27, v23
	s_nop 0
	v_pk_mul_f32 v[24:25], v[26:27], v[24:25]
	s_nop 0
	v_pk_mul_f32 v[20:21], v[20:21], v[24:25]
	s_nop 0
	v_cvt_pk_bf16_f32 v23, v20, v21
	global_store_dwordx2 v[32:33], v[22:23], off offset:1568
	s_nop 0
	s_waitcnt vmcnt(3)
	v_lshlrev_b32_e32 v22, 16, v240
	v_and_b32_e32 v23, 0xffff0000, v240
	v_mul_f32_e32 v24, 0xbfb8aa3b, v22
	v_mul_f32_e32 v25, 0xbfb8aa3b, v23
	v_exp_f32_e32 v24, v24
	v_exp_f32_e32 v25, v25
	v_lshlrev_b32_e32 v20, 16, v241
	v_and_b32_e32 v21, 0xffff0000, v241
	v_add_f32_e32 v24, 1.0, v24
	v_add_f32_e32 v25, 1.0, v25
	v_rcp_f32_e32 v24, v24
	v_rcp_f32_e32 v25, v25
	s_nop 0
	v_pk_mul_f32 v[22:23], v[24:25], v[22:23]
	s_nop 0
	v_pk_mul_f32 v[18:19], v[18:19], v[22:23]
	s_nop 0
	v_cvt_pk_bf16_f32 v18, v18, v19
	v_mul_f32_e32 v19, 0xbfb8aa3b, v20
	v_exp_f32_e32 v19, v19
	s_nop 0
	v_add_f32_e32 v19, 1.0, v19
	v_rcp_f32_e32 v22, v19
	v_mul_f32_e32 v19, 0xbfb8aa3b, v21
	v_exp_f32_e32 v19, v19
	s_nop 0
	v_add_f32_e32 v19, 1.0, v19
	v_rcp_f32_e32 v23, v19
	s_nop 0
	v_pk_mul_f32 v[20:21], v[22:23], v[20:21]
	s_nop 0
	v_pk_mul_f32 v[16:17], v[16:17], v[20:21]
	s_nop 0
	v_cvt_pk_bf16_f32 v19, v16, v17
	global_store_dwordx2 v[32:33], v[18:19], off offset:1584
	s_nop 0
	s_waitcnt vmcnt(4)
; DI float lo_bf(unsigned w) { return __uint_as_float(w << 16); }
; DI float hi_bf(unsigned w) { return __uint_as_float(w & 0xffff0000u); }
; DI float siluf_(float x) { return x * __builtin_amdgcn_rcpf(1.f + __builtin_amdgcn_exp2f(-1.4426950408889634f * x)); }
; template <int TYPE>
; DI void attn_item(const Params& p, int l, int bb, int head, int qb, char* smem) {
;     ...
; #pragma unroll
;   for (int d = 0; d < 2; d++)
; #pragma unroll
;     for (int g = 0; g < 4; g++) {
;       int dv0 = d * 32 + 8 * g + 4 * h2;
;       u32x2 gw = *(const u32x2*)(p.Gs + mh * 1024 + gcol + head * 64 + dv0);
;       float g0 = lo_bf(gw.x), g1 = hi_bf(gw.x), g2 = lo_bf(gw.y), g3 = hi_bf(gw.y);
;       u32x2 ow;
;       ow.x = pack2(val[d][4 * g] * siluf_(g0), val[d][4 * g + 1] * siluf_(g1));
;       ow.y = pack2(val[d][4 * g + 2] * siluf_(g2), val[d][4 * g + 3] * siluf_(g3));
;       *(u32x2*)(p.o + mh * DM + ocol + head * 64 + dv0) = ow;
;     }
	v_lshlrev_b32_e32 v18, 16, v242
	v_and_b32_e32 v19, 0xffff0000, v242
	v_mul_f32_e32 v20, 0xbfb8aa3b, v18
	v_mul_f32_e32 v21, 0xbfb8aa3b, v19
	v_exp_f32_e32 v20, v20
	v_exp_f32_e32 v21, v21
	v_lshlrev_b32_e32 v16, 16, v243
	v_and_b32_e32 v17, 0xffff0000, v243
	v_add_f32_e32 v20, 1.0, v20
	v_add_f32_e32 v21, 1.0, v21
	v_rcp_f32_e32 v20, v20
	v_rcp_f32_e32 v21, v21
	s_nop 0
	v_pk_mul_f32 v[18:19], v[20:21], v[18:19]
	s_nop 0
	v_pk_mul_f32 v[14:15], v[14:15], v[18:19]
	s_nop 0
	v_cvt_pk_bf16_f32 v14, v14, v15
	v_mul_f32_e32 v15, 0xbfb8aa3b, v16
	v_exp_f32_e32 v15, v15
	s_nop 0
	v_add_f32_e32 v15, 1.0, v15
	v_rcp_f32_e32 v18, v15
	v_mul_f32_e32 v15, 0xbfb8aa3b, v17
	v_exp_f32_e32 v15, v15
	s_nop 0
	v_add_f32_e32 v15, 1.0, v15
	v_rcp_f32_e32 v19, v15
	s_nop 0
	v_pk_mul_f32 v[16:17], v[18:19], v[16:17]
	s_nop 0
	v_pk_mul_f32 v[12:13], v[12:13], v[16:17]
	s_nop 0
	v_cvt_pk_bf16_f32 v15, v12, v13
	global_store_dwordx2 v[32:33], v[14:15], off offset:1600
	s_nop 0
	s_waitcnt vmcnt(5)
	v_lshlrev_b32_e32 v14, 16, v244
	v_and_b32_e32 v15, 0xffff0000, v244
	v_mul_f32_e32 v16, 0xbfb8aa3b, v14
	v_mul_f32_e32 v17, 0xbfb8aa3b, v15
	v_exp_f32_e32 v16, v16
	v_exp_f32_e32 v17, v17
	v_lshlrev_b32_e32 v12, 16, v245
	v_and_b32_e32 v13, 0xffff0000, v245
	v_add_f32_e32 v16, 1.0, v16
	v_add_f32_e32 v17, 1.0, v17
	v_rcp_f32_e32 v16, v16
	v_rcp_f32_e32 v17, v17
	s_nop 0
	v_pk_mul_f32 v[14:15], v[16:17], v[14:15]
	s_nop 0
	v_pk_mul_f32 v[10:11], v[10:11], v[14:15]
	s_nop 0
	v_cvt_pk_bf16_f32 v10, v10, v11
	v_mul_f32_e32 v11, 0xbfb8aa3b, v12
	v_exp_f32_e32 v11, v11
	s_nop 0
	v_add_f32_e32 v11, 1.0, v11
	v_rcp_f32_e32 v14, v11
	v_mul_f32_e32 v11, 0xbfb8aa3b, v13
	v_exp_f32_e32 v11, v11
	s_nop 0
	v_add_f32_e32 v11, 1.0, v11
	v_rcp_f32_e32 v15, v11
	s_nop 0
	v_pk_mul_f32 v[12:13], v[14:15], v[12:13]
	s_nop 0
	v_pk_mul_f32 v[8:9], v[8:9], v[12:13]
	s_nop 0
	v_cvt_pk_bf16_f32 v11, v8, v9
	global_store_dwordx2 v[32:33], v[10:11], off offset:1616
	s_nop 0
	s_waitcnt vmcnt(6)
	v_lshlrev_b32_e32 v10, 16, v246
	v_and_b32_e32 v11, 0xffff0000, v246
	v_mul_f32_e32 v12, 0xbfb8aa3b, v10
	v_mul_f32_e32 v13, 0xbfb8aa3b, v11
	v_exp_f32_e32 v12, v12
	v_exp_f32_e32 v13, v13
	v_lshlrev_b32_e32 v8, 16, v247
	v_and_b32_e32 v9, 0xffff0000, v247
	v_add_f32_e32 v12, 1.0, v12
	v_add_f32_e32 v13, 1.0, v13
	v_rcp_f32_e32 v12, v12
	v_rcp_f32_e32 v13, v13
	s_nop 0
	v_pk_mul_f32 v[10:11], v[12:13], v[10:11]
	s_nop 0
	v_pk_mul_f32 v[6:7], v[6:7], v[10:11]
	s_nop 0
	v_cvt_pk_bf16_f32 v6, v6, v7
	v_mul_f32_e32 v7, 0xbfb8aa3b, v8
	v_exp_f32_e32 v7, v7
	s_nop 0
	v_add_f32_e32 v7, 1.0, v7
	v_rcp_f32_e32 v10, v7
	v_mul_f32_e32 v7, 0xbfb8aa3b, v9
	v_exp_f32_e32 v7, v7
	s_nop 0
	v_add_f32_e32 v7, 1.0, v7
	v_rcp_f32_e32 v11, v7
	s_nop 0
	v_pk_mul_f32 v[8:9], v[10:11], v[8:9]
	s_nop 0
	v_pk_mul_f32 v[4:5], v[4:5], v[8:9]
	s_nop 0
	v_cvt_pk_bf16_f32 v7, v4, v5
	global_store_dwordx2 v[32:33], v[6:7], off offset:1632
	s_nop 0
	s_waitcnt vmcnt(7)
	v_lshlrev_b32_e32 v6, 16, v248
	v_and_b32_e32 v7, 0xffff0000, v248
	v_mul_f32_e32 v8, 0xbfb8aa3b, v6
	v_mul_f32_e32 v9, 0xbfb8aa3b, v7
	v_exp_f32_e32 v8, v8
	v_exp_f32_e32 v9, v9
	v_lshlrev_b32_e32 v4, 16, v249
	v_and_b32_e32 v5, 0xffff0000, v249
	v_add_f32_e32 v8, 1.0, v8
	v_add_f32_e32 v9, 1.0, v9
	v_rcp_f32_e32 v8, v8
	v_rcp_f32_e32 v9, v9
	s_nop 0
	v_pk_mul_f32 v[6:7], v[8:9], v[6:7]
	s_nop 0
	v_pk_mul_f32 v[2:3], v[2:3], v[6:7]
	s_nop 0
	v_cvt_pk_bf16_f32 v2, v2, v3
	v_mul_f32_e32 v3, 0xbfb8aa3b, v4
	v_exp_f32_e32 v3, v3
	s_nop 0
	v_add_f32_e32 v3, 1.0, v3
	v_rcp_f32_e32 v6, v3
	v_mul_f32_e32 v3, 0xbfb8aa3b, v5
	v_exp_f32_e32 v3, v3
	s_nop 0
	v_add_f32_e32 v3, 1.0, v3
	v_rcp_f32_e32 v7, v3
	s_nop 0
	v_pk_mul_f32 v[4:5], v[6:7], v[4:5]
	s_nop 0
	v_pk_mul_f32 v[0:1], v[0:1], v[4:5]
	s_nop 0
	v_cvt_pk_bf16_f32 v3, v0, v1
	global_store_dwordx2 v[32:33], v[2:3], off offset:1648

; #define MFMA32(a, b, c) __builtin_amdgcn_mfma_f32_32x32x16_bf16((a), (b), (c), 0, 0, 0)
; DI int otid() { int t; asm volatile("v_mov_b32 %0, %1" : "=v"(t) : "v"((int)threadIdx.x)); return t; }
; DI float xsum32(float x) { auto r = __builtin_amdgcn_permlane32_swap(__float_as_uint(x), __float_as_uint(x), false, false); return __uint_as_float(r[0]) + __uint_as_float(r[1]); }
; template <int TYPE>
; DI void attn_item(const Params& p, int l, int bb, int head, int qb, char* smem) {
;     ...
; #pragma unroll
;         for (int kb = 0; kb < 2; kb++)
; #pragma unroll
;           for (int i = 0; i < 16; i++) { float e = __builtin_amdgcn_exp2f(s[kb][i]); s[kb][i] = e; psum += e; }
;       }
;       lrun[mp] += psum;
; #pragma unroll
;       for (int kb = 0; kb < 2; kb++)
; #pragma unroll
;         for (int s2 = 0; s2 < 2; s2++) {
;           unsigned pw[4];
; #pragma unroll
;           for (int e = 0; e < 4; e++) pw[e] = pack2(s[kb][8 * s2 + 2 * e], s[kb][8 * s2 + 2 * e + 1]);
;           u32x4 pu = u32x4{pw[0], pw[1], pw[2], pw[3]};
;           bf16x8 pf = __builtin_bit_cast(bf16x8, pu);
; #pragma unroll
;           for (int d = 0; d < 2; d++) {
;             const u16* vp = sV + (d * 32 + r) * 72 + kb * 32 + s2 * 16 + 4 * h;
;             s16x4 vlo = *(const s16x4*)vp, vhi = *(const s16x4*)(vp + 8);
;             bf16x8 vf = __builtin_shufflevector(vlo, vhi, 0, 1, 2, 3, 4, 5, 6, 7);
;             O[mp][d] = MFMA32(vf, pf, O[mp][d]);
;           }
;         }
;     }
;     __syncthreads();
;   }
;   float inv[NMAP];
; #pragma unroll
;   for (int mp = 0; mp < NMAP; mp++) { float lt = xsum32(lrun[mp]); inv[mp] = 1.f / lt; }
;   const int tid2 = otid();
;   const int r2 = tid2 & 31, h2 = (tid2 >> 5) & 1, wv2 = tid2 >> 6;
;   const int t = qb * 128 + wv2 * 32 + r2;
;   const long mh = (long)bb * T + t;
;     ...
; #pragma unroll
;     for (int d = 0; d < 2; d++)
; #pragma unroll
;       for (int i = 0; i < 16; i++) val[d][i] = O[0][d][i] * inv[0];
;   }
; #pragma unroll
;   for (int d = 0; d < 2; d++)
; #pragma unroll
;     for (int g = 0; g < 4; g++) {
;       int dv0 = d * 32 + 8 * g + 4 * h2;
;       u32x2 gw = *(const u32x2*)(p.Gs + mh * 1024 + gcol + head * 64 + dv0);
.LBB0_386:
	v_exp_f32_e32 v48, v48
	v_exp_f32_e32 v49, v49
	v_exp_f32_e32 v50, v50
	v_exp_f32_e32 v51, v51
	v_add_f32_e32 v64, 0, v48
	v_exp_f32_e32 v52, v52
	v_add_f32_e32 v64, v64, v49
	v_exp_f32_e32 v53, v53
	v_add_f32_e32 v64, v50, v64
	v_exp_f32_e32 v54, v54
	v_add_f32_e32 v64, v51, v64
	v_exp_f32_e32 v55, v55
	v_add_f32_e32 v64, v52, v64
	v_exp_f32_e32 v56, v56
	v_add_f32_e32 v64, v53, v64
	v_exp_f32_e32 v57, v57
	v_add_f32_e32 v64, v54, v64
	v_exp_f32_e32 v58, v58
	v_add_f32_e32 v64, v55, v64
	v_exp_f32_e32 v59, v59
	v_add_f32_e32 v64, v56, v64
	v_exp_f32_e32 v60, v60
	v_add_f32_e32 v64, v57, v64
	v_exp_f32_e32 v61, v61
	v_add_f32_e32 v64, v58, v64
	v_exp_f32_e32 v62, v62
	v_add_f32_e32 v64, v59, v64
	v_exp_f32_e32 v63, v63
	v_add_f32_e32 v64, v60, v64
	v_exp_f32_e32 v65, v32
	v_add_f32_e32 v64, v61, v64
	v_add_f32_e32 v64, v62, v64
	v_add_f32_e32 v64, v63, v64
	v_add_f32_e32 v32, v65, v64
	v_exp_f32_e32 v64, v33
	v_exp_f32_e32 v66, v34
	v_exp_f32_e32 v67, v35
	v_exp_f32_e32 v68, v36
	v_add_f32_e32 v32, v64, v32
	v_exp_f32_e32 v69, v37
	v_add_f32_e32 v32, v66, v32
	v_exp_f32_e32 v70, v38
	v_add_f32_e32 v32, v67, v32
	v_exp_f32_e32 v71, v39
	v_add_f32_e32 v32, v68, v32
	v_exp_f32_e32 v72, v40
	v_add_f32_e32 v32, v69, v32
	v_exp_f32_e32 v73, v41
	v_add_f32_e32 v32, v70, v32
	v_exp_f32_e32 v74, v42
	v_add_f32_e32 v32, v71, v32
	v_exp_f32_e32 v75, v43
	v_add_f32_e32 v32, v72, v32
	v_exp_f32_e32 v44, v44
	v_add_f32_e32 v32, v73, v32
	v_exp_f32_e32 v45, v45
	v_add_f32_e32 v32, v74, v32
	v_exp_f32_e32 v46, v46
	v_add_f32_e32 v32, v75, v32
	v_exp_f32_e32 v47, v47
	v_add_f32_e32 v32, v44, v32
	ds_read2_b64 v[36:39], v80 offset0:128 offset1:130
	ds_read2_b64 v[40:43], v80 offset0:132 offset1:134
	v_add_f32_e32 v32, v45, v32
	v_add_f32_e32 v32, v46, v32
	v_add_f32_e32 v76, v47, v32
	v_cvt_pk_bf16_f32 v32, v48, v49
	v_cvt_pk_bf16_f32 v33, v50, v51
	v_cvt_pk_bf16_f32 v34, v52, v53
	v_cvt_pk_bf16_f32 v35, v54, v55
	s_mul_i32 s26, s37, 0x1100
	v_readlane_b32 s40, v254, 18
	s_waitcnt lgkmcnt(1)
	v_mfma_f32_32x32x16_bf16 v[16:31], v[36:39], v[32:35], v[16:31]
	ds_read2_b64 v[36:39], v81 offset0:192 offset1:194
	v_readlane_b32 s41, v254, 19
	v_readlane_b32 s42, v254, 20
	v_readlane_b32 s43, v254, 21
	s_waitcnt lgkmcnt(0)
	v_mfma_f32_32x32x16_bf16 v[0:15], v[36:39], v[32:35], v[0:15]
	ds_read2_b64 v[36:39], v81 offset0:196 offset1:198
	v_cvt_pk_bf16_f32 v32, v56, v57
	v_cvt_pk_bf16_f32 v33, v58, v59
	v_cvt_pk_bf16_f32 v34, v60, v61
	v_cvt_pk_bf16_f32 v35, v62, v63
	s_waitcnt lgkmcnt(0)
	s_nop 0
	v_mfma_f32_32x32x16_bf16 v[0:15], v[36:39], v[32:35], v[0:15]
	ds_read2_b64 v[36:39], v80 offset0:136 offset1:138
	v_mfma_f32_32x32x16_bf16 v[16:31], v[40:43], v[32:35], v[16:31]
	v_cvt_pk_bf16_f32 v32, v65, v64
	v_cvt_pk_bf16_f32 v33, v66, v67
	v_cvt_pk_bf16_f32 v34, v68, v69
	v_cvt_pk_bf16_f32 v35, v70, v71
	s_waitcnt lgkmcnt(0)
	s_nop 0
	v_mfma_f32_32x32x16_bf16 v[16:31], v[36:39], v[32:35], v[16:31]
	ds_read2_b64 v[36:39], v81 offset0:200 offset1:202
	s_waitcnt lgkmcnt(0)
	v_mfma_f32_32x32x16_bf16 v[0:15], v[36:39], v[32:35], v[0:15]
	ds_read2_b64 v[36:39], v80 offset0:140 offset1:142
	v_cvt_pk_bf16_f32 v32, v72, v73
	v_cvt_pk_bf16_f32 v33, v74, v75
	v_cvt_pk_bf16_f32 v34, v44, v45
	v_cvt_pk_bf16_f32 v35, v46, v47
	s_waitcnt lgkmcnt(0)
	s_nop 0
	v_mfma_f32_32x32x16_bf16 v[16:31], v[36:39], v[32:35], v[16:31]
	ds_read2_b64 v[36:39], v81 offset0:204 offset1:206
	s_waitcnt lgkmcnt(0)
	s_barrier
	v_mfma_f32_32x32x16_bf16 v[0:15], v[36:39], v[32:35], v[0:15]
	v_add_f32_e32 v32, v136, v76
	v_mov_b32_e32 v33, v32
	s_nop 1
	v_permlane32_swap_b32_e32 v32, v33
	v_add_f32_e32 v32, v32, v33
	v_div_scale_f32 v33, s[12:13], v32, v32, 1.0
	v_rcp_f32_e32 v34, v33
	s_nop 0
	v_fma_f32 v35, -v33, v34, 1.0
	v_fmac_f32_e32 v34, v35, v34
	v_div_scale_f32 v35, vcc, 1.0, v32, 1.0
	v_mul_f32_e32 v36, v35, v34
	v_fma_f32 v37, -v33, v36, v35
	v_fmac_f32_e32 v36, v37, v34
	v_fma_f32 v33, -v33, v36, v35
	v_div_fmas_f32 v33, v33, v34, v36
	v_div_fixup_f32 v32, v33, v32, 1.0
	v_mov_b32 v33, v198
	s_nop 0
	v_ashrrev_i32_e32 v34, 1, v33
	v_and_b32_e32 v34, 0xffffffe0, v34
	v_add_u32_e32 v34, s38, v34
	v_and_or_b32 v34, v33, 31, v34
	v_ashrrev_i32_e32 v35, 31, v34
	v_lshl_add_u64 v[34:35], v[34:35], 0, s[26:27]
	v_lshlrev_b64 v[36:37], 11, v[34:35]
	v_lshl_add_u64 v[34:35], s[94:95], 0, v[36:37]
	s_lshl_b32 s26, s36, 7
	v_lshrrev_b32_e32 v33, 2, v33
	v_lshl_add_u64 v[34:35], v[34:35], 0, s[26:27]
	v_and_b32_e32 v176, 8, v33
	v_lshl_add_u64 v[34:35], v[34:35], 0, v[176:177]
	global_load_dwordx2 v[38:39], v[34:35], off offset:1024
	global_load_dwordx2 v[236:237], v[34:35], off offset:1040
	global_load_dwordx2 v[238:239], v[34:35], off offset:1056
	global_load_dwordx2 v[240:241], v[34:35], off offset:1072
	global_load_dwordx2 v[242:243], v[34:35], off offset:1088
	global_load_dwordx2 v[244:245], v[34:35], off offset:1104
	global_load_dwordx2 v[246:247], v[34:35], off offset:1120
	global_load_dwordx2 v[248:249], v[34:35], off offset:1136
	v_pk_mul_f32 v[16:17], v[16:17], v[32:33] op_sel_hi:[1, 0]
	s_waitcnt vmcnt(7)
; DI float lo_bf(unsigned w) { return __uint_as_float(w << 16); }
; DI float hi_bf(unsigned w) { return __uint_as_float(w & 0xffff0000u); }
; DI float siluf_(float x) { return x * __builtin_amdgcn_rcpf(1.f + __builtin_amdgcn_exp2f(-1.4426950408889634f * x)); }
; template <int TYPE>
; DI void attn_item(const Params& p, int l, int bb, int head, int qb, char* smem) {
;     ...
; #pragma unroll
;     for (int d = 0; d < 2; d++)
; #pragma unroll
;       for (int i = 0; i < 16; i++) val[d][i] = O[0][d][i] * inv[0];
;   }
; #pragma unroll
;   for (int d = 0; d < 2; d++)
; #pragma unroll
;     for (int g = 0; g < 4; g++) {
;       int dv0 = d * 32 + 8 * g + 4 * h2;
;       u32x2 gw = *(const u32x2*)(p.Gs + mh * 1024 + gcol + head * 64 + dv0);
;       float g0 = lo_bf(gw.x), g1 = hi_bf(gw.x), g2 = lo_bf(gw.y), g3 = hi_bf(gw.y);
;       u32x2 ow;
;       ow.x = pack2(val[d][4 * g] * siluf_(g0), val[d][4 * g + 1] * siluf_(g1));
;       ow.y = pack2(val[d][4 * g + 2] * siluf_(g2), val[d][4 * g + 3] * siluf_(g3));
;       *(u32x2*)(p.o + mh * DM + ocol + head * 64 + dv0) = ow;
;     }
	v_lshlrev_b32_e32 v40, 16, v38
	v_mul_f32_e32 v33, 0xbfb8aa3b, v40
	v_exp_f32_e32 v33, v33
	v_and_b32_e32 v41, 0xffff0000, v38
	v_add_f32_e32 v33, 1.0, v33
	v_rcp_f32_e32 v42, v33
	v_mul_f32_e32 v33, 0xbfb8aa3b, v41
	v_exp_f32_e32 v33, v33
	s_nop 0
	v_add_f32_e32 v33, 1.0, v33
	v_rcp_f32_e32 v43, v33
	s_nop 0
	v_pk_mul_f32 v[40:41], v[42:43], v[40:41]
	s_nop 0
	v_pk_mul_f32 v[16:17], v[16:17], v[40:41]
	s_nop 0
	v_cvt_pk_bf16_f32 v38, v16, v17
	v_pk_mul_f32 v[16:17], v[18:19], v[32:33] op_sel_hi:[1, 0]
	v_lshlrev_b32_e32 v18, 16, v39
	v_mul_f32_e32 v33, 0xbfb8aa3b, v18
	v_exp_f32_e32 v33, v33
	v_and_b32_e32 v19, 0xffff0000, v39
	v_add_f32_e32 v33, 1.0, v33
	v_rcp_f32_e32 v40, v33
	v_mul_f32_e32 v33, 0xbfb8aa3b, v19
	v_exp_f32_e32 v33, v33
	s_nop 0
	v_add_f32_e32 v33, 1.0, v33
	v_rcp_f32_e32 v41, v33
	v_pk_mul_f32 v[20:21], v[20:21], v[32:33] op_sel_hi:[1, 0]
	v_pk_mul_f32 v[0:1], v[0:1], v[32:33] op_sel_hi:[1, 0]
	v_pk_mul_f32 v[2:3], v[2:3], v[32:33] op_sel_hi:[1, 0]
	v_pk_mul_f32 v[18:19], v[40:41], v[18:19]
	s_nop 0
	v_pk_mul_f32 v[16:17], v[16:17], v[18:19]
	s_nop 0
	v_cvt_pk_bf16_f32 v39, v16, v17
	v_lshl_add_u64 v[16:17], s[40:41], 0, v[36:37]
	v_lshl_add_u64 v[16:17], v[16:17], 0, s[26:27]
	v_lshl_add_u64 v[16:17], v[16:17], 0, v[176:177]
	global_store_dwordx2 v[16:17], v[38:39], off offset:1024
	s_nop 0
	s_waitcnt vmcnt(7)
	v_lshlrev_b32_e32 v36, 16, v236
	v_and_b32_e32 v37, 0xffff0000, v236
	v_mul_f32_e32 v18, 0xbfb8aa3b, v36
	v_exp_f32_e32 v18, v18
	s_nop 0
	v_add_f32_e32 v18, 1.0, v18
	v_rcp_f32_e32 v38, v18
	v_mul_f32_e32 v18, 0xbfb8aa3b, v37
	v_exp_f32_e32 v18, v18
	s_nop 0
	v_add_f32_e32 v18, 1.0, v18
	v_rcp_f32_e32 v39, v18
	s_nop 0
	v_pk_mul_f32 v[36:37], v[38:39], v[36:37]
	s_nop 0
	v_pk_mul_f32 v[20:21], v[20:21], v[36:37]
	s_nop 0
	v_cvt_pk_bf16_f32 v18, v20, v21
	v_pk_mul_f32 v[20:21], v[22:23], v[32:33] op_sel_hi:[1, 0]
	v_lshlrev_b32_e32 v22, 16, v237
	v_and_b32_e32 v23, 0xffff0000, v237
	v_mul_f32_e32 v19, 0xbfb8aa3b, v22
	v_exp_f32_e32 v19, v19
	s_nop 0
	v_add_f32_e32 v19, 1.0, v19
	v_rcp_f32_e32 v36, v19
	v_mul_f32_e32 v19, 0xbfb8aa3b, v23
	v_exp_f32_e32 v19, v19
	s_nop 0
	v_add_f32_e32 v19, 1.0, v19
	v_rcp_f32_e32 v37, v19
	s_nop 0
	v_pk_mul_f32 v[22:23], v[36:37], v[22:23]
	s_nop 0
	v_pk_mul_f32 v[20:21], v[20:21], v[22:23]
	s_nop 0
	v_cvt_pk_bf16_f32 v19, v20, v21
	global_store_dwordx2 v[16:17], v[18:19], off offset:1040
	s_nop 0
	v_pk_mul_f32 v[20:21], v[24:25], v[32:33] op_sel_hi:[1, 0]
	s_waitcnt vmcnt(7)
	v_lshlrev_b32_e32 v22, 16, v238
	v_and_b32_e32 v23, 0xffff0000, v238
	v_mul_f32_e32 v18, 0xbfb8aa3b, v22
	v_exp_f32_e32 v18, v18
	s_nop 0
	v_add_f32_e32 v18, 1.0, v18
	v_rcp_f32_e32 v24, v18
	v_mul_f32_e32 v18, 0xbfb8aa3b, v23
	v_exp_f32_e32 v18, v18
	s_nop 0
	v_add_f32_e32 v18, 1.0, v18
	v_rcp_f32_e32 v25, v18
	s_nop 0
	v_pk_mul_f32 v[22:23], v[24:25], v[22:23]
	s_nop 0
	v_pk_mul_f32 v[20:21], v[20:21], v[22:23]
	v_lshlrev_b32_e32 v22, 16, v239
	v_and_b32_e32 v23, 0xffff0000, v239
	v_mul_f32_e32 v19, 0xbfb8aa3b, v22
	v_exp_f32_e32 v19, v19
	v_cvt_pk_bf16_f32 v18, v20, v21
	v_pk_mul_f32 v[20:21], v[26:27], v[32:33] op_sel_hi:[1, 0]
	v_add_f32_e32 v19, 1.0, v19
	v_rcp_f32_e32 v24, v19
	v_mul_f32_e32 v19, 0xbfb8aa3b, v23
	v_exp_f32_e32 v19, v19
	s_nop 0
	v_add_f32_e32 v19, 1.0, v19
	v_rcp_f32_e32 v25, v19
	s_nop 0
	v_pk_mul_f32 v[22:23], v[24:25], v[22:23]
	s_nop 0
	v_pk_mul_f32 v[20:21], v[20:21], v[22:23]
	s_nop 0
	v_cvt_pk_bf16_f32 v19, v20, v21
	global_store_dwordx2 v[16:17], v[18:19], off offset:1056
	s_nop 0
	v_pk_mul_f32 v[20:21], v[28:29], v[32:33] op_sel_hi:[1, 0]
	s_waitcnt vmcnt(7)
	v_lshlrev_b32_e32 v22, 16, v240
	v_and_b32_e32 v23, 0xffff0000, v240
	v_mul_f32_e32 v18, 0xbfb8aa3b, v22
	v_exp_f32_e32 v18, v18
	s_nop 0
	v_add_f32_e32 v18, 1.0, v18
	v_rcp_f32_e32 v24, v18
	v_mul_f32_e32 v18, 0xbfb8aa3b, v23
	v_exp_f32_e32 v18, v18
	s_nop 0
	v_add_f32_e32 v18, 1.0, v18
	v_rcp_f32_e32 v25, v18
	s_nop 0
	v_pk_mul_f32 v[22:23], v[24:25], v[22:23]
	s_nop 0
	v_pk_mul_f32 v[20:21], v[20:21], v[22:23]
	v_lshlrev_b32_e32 v22, 16, v241
	v_and_b32_e32 v23, 0xffff0000, v241
	v_mul_f32_e32 v19, 0xbfb8aa3b, v22
	v_exp_f32_e32 v19, v19
	v_cvt_pk_bf16_f32 v18, v20, v21
	v_pk_mul_f32 v[20:21], v[30:31], v[32:33] op_sel_hi:[1, 0]
	v_add_f32_e32 v19, 1.0, v19
	v_rcp_f32_e32 v24, v19
	v_mul_f32_e32 v19, 0xbfb8aa3b, v23
	v_exp_f32_e32 v19, v19
	s_nop 0
	v_add_f32_e32 v19, 1.0, v19
	v_rcp_f32_e32 v25, v19
	s_nop 0
	v_pk_mul_f32 v[22:23], v[24:25], v[22:23]
	s_nop 0
	v_pk_mul_f32 v[20:21], v[20:21], v[22:23]
	s_nop 0
	v_cvt_pk_bf16_f32 v19, v20, v21
	global_store_dwordx2 v[16:17], v[18:19], off offset:1072
	s_nop 0
	s_waitcnt vmcnt(7)
; DI float lo_bf(unsigned w) { return __uint_as_float(w << 16); }
; DI float hi_bf(unsigned w) { return __uint_as_float(w & 0xffff0000u); }
; DI float siluf_(float x) { return x * __builtin_amdgcn_rcpf(1.f + __builtin_amdgcn_exp2f(-1.4426950408889634f * x)); }
; template <int TYPE>
; DI void attn_item(const Params& p, int l, int bb, int head, int qb, char* smem) {
;     ...
; #pragma unroll
;   for (int d = 0; d < 2; d++)
; #pragma unroll
;     for (int g = 0; g < 4; g++) {
;       int dv0 = d * 32 + 8 * g + 4 * h2;
;       u32x2 gw = *(const u32x2*)(p.Gs + mh * 1024 + gcol + head * 64 + dv0);
;       float g0 = lo_bf(gw.x), g1 = hi_bf(gw.x), g2 = lo_bf(gw.y), g3 = hi_bf(gw.y);
;       u32x2 ow;
;       ow.x = pack2(val[d][4 * g] * siluf_(g0), val[d][4 * g + 1] * siluf_(g1));
;       ow.y = pack2(val[d][4 * g + 2] * siluf_(g2), val[d][4 * g + 3] * siluf_(g3));
;       *(u32x2*)(p.o + mh * DM + ocol + head * 64 + dv0) = ow;
;     }
	v_lshlrev_b32_e32 v20, 16, v242
	v_and_b32_e32 v21, 0xffff0000, v242
	v_mul_f32_e32 v18, 0xbfb8aa3b, v20
	v_exp_f32_e32 v18, v18
	s_nop 0
	v_add_f32_e32 v18, 1.0, v18
	v_rcp_f32_e32 v22, v18
	v_mul_f32_e32 v18, 0xbfb8aa3b, v21
	v_exp_f32_e32 v18, v18
	s_nop 0
	v_add_f32_e32 v18, 1.0, v18
	v_rcp_f32_e32 v23, v18
	v_lshlrev_b32_e32 v18, 16, v243
	v_and_b32_e32 v19, 0xffff0000, v243
	v_pk_mul_f32 v[20:21], v[22:23], v[20:21]
	s_nop 0
	v_pk_mul_f32 v[0:1], v[0:1], v[20:21]
	s_nop 0
	v_cvt_pk_bf16_f32 v0, v0, v1
	v_mul_f32_e32 v1, 0xbfb8aa3b, v18
	v_exp_f32_e32 v1, v1
	s_nop 0
	v_add_f32_e32 v1, 1.0, v1
	v_rcp_f32_e32 v20, v1
	v_mul_f32_e32 v1, 0xbfb8aa3b, v19
	v_exp_f32_e32 v1, v1
	s_nop 0
	v_add_f32_e32 v1, 1.0, v1
	v_rcp_f32_e32 v21, v1
	s_nop 0
	v_pk_mul_f32 v[18:19], v[20:21], v[18:19]
	s_nop 0
	v_pk_mul_f32 v[2:3], v[2:3], v[18:19]
	s_nop 0
	v_cvt_pk_bf16_f32 v1, v2, v3
	global_store_dwordx2 v[16:17], v[0:1], off offset:1088
	s_nop 0
	v_pk_mul_f32 v[2:3], v[4:5], v[32:33] op_sel_hi:[1, 0]
	s_waitcnt vmcnt(7)
	v_lshlrev_b32_e32 v4, 16, v244
	v_and_b32_e32 v5, 0xffff0000, v244
	v_mul_f32_e32 v0, 0xbfb8aa3b, v4
	v_exp_f32_e32 v0, v0
	s_nop 0
	v_add_f32_e32 v0, 1.0, v0
	v_rcp_f32_e32 v18, v0
	v_mul_f32_e32 v0, 0xbfb8aa3b, v5
	v_exp_f32_e32 v0, v0
	s_nop 0
	v_add_f32_e32 v0, 1.0, v0
	v_rcp_f32_e32 v19, v0
	s_nop 0
	v_pk_mul_f32 v[4:5], v[18:19], v[4:5]
	s_nop 0
	v_pk_mul_f32 v[2:3], v[2:3], v[4:5]
	v_lshlrev_b32_e32 v4, 16, v245
	v_and_b32_e32 v5, 0xffff0000, v245
	v_mul_f32_e32 v1, 0xbfb8aa3b, v4
	v_exp_f32_e32 v1, v1
	v_cvt_pk_bf16_f32 v0, v2, v3
	v_pk_mul_f32 v[2:3], v[6:7], v[32:33] op_sel_hi:[1, 0]
	v_add_f32_e32 v1, 1.0, v1
	v_rcp_f32_e32 v6, v1
	v_mul_f32_e32 v1, 0xbfb8aa3b, v5
	v_exp_f32_e32 v1, v1
	s_nop 0
	v_add_f32_e32 v1, 1.0, v1
	v_rcp_f32_e32 v7, v1
	s_nop 0
	v_pk_mul_f32 v[4:5], v[6:7], v[4:5]
	s_nop 0
	v_pk_mul_f32 v[2:3], v[2:3], v[4:5]
	s_nop 0
	v_cvt_pk_bf16_f32 v1, v2, v3
	global_store_dwordx2 v[16:17], v[0:1], off offset:1104
	s_nop 0
	v_pk_mul_f32 v[2:3], v[8:9], v[32:33] op_sel_hi:[1, 0]
	s_waitcnt vmcnt(7)
	v_lshlrev_b32_e32 v4, 16, v246
	v_and_b32_e32 v5, 0xffff0000, v246
	v_mul_f32_e32 v0, 0xbfb8aa3b, v4
	v_exp_f32_e32 v0, v0
	s_nop 0
	v_add_f32_e32 v0, 1.0, v0
	v_rcp_f32_e32 v6, v0
	v_mul_f32_e32 v0, 0xbfb8aa3b, v5
	v_exp_f32_e32 v0, v0
	s_nop 0
	v_add_f32_e32 v0, 1.0, v0
	v_rcp_f32_e32 v7, v0
	s_nop 0
	v_pk_mul_f32 v[4:5], v[6:7], v[4:5]
	s_nop 0
	v_pk_mul_f32 v[2:3], v[2:3], v[4:5]
	v_lshlrev_b32_e32 v4, 16, v247
	v_and_b32_e32 v5, 0xffff0000, v247
	v_mul_f32_e32 v1, 0xbfb8aa3b, v4
	v_exp_f32_e32 v1, v1
	v_cvt_pk_bf16_f32 v0, v2, v3
	v_pk_mul_f32 v[2:3], v[10:11], v[32:33] op_sel_hi:[1, 0]
	v_add_f32_e32 v1, 1.0, v1
	v_rcp_f32_e32 v6, v1
	v_mul_f32_e32 v1, 0xbfb8aa3b, v5
	v_exp_f32_e32 v1, v1
	s_nop 0
	v_add_f32_e32 v1, 1.0, v1
	v_rcp_f32_e32 v7, v1
	s_nop 0
	v_pk_mul_f32 v[4:5], v[6:7], v[4:5]
	s_nop 0
	v_pk_mul_f32 v[2:3], v[2:3], v[4:5]
	s_nop 0
	v_cvt_pk_bf16_f32 v1, v2, v3
	global_store_dwordx2 v[16:17], v[0:1], off offset:1120
	s_nop 0
	v_pk_mul_f32 v[2:3], v[12:13], v[32:33] op_sel_hi:[1, 0]
	s_waitcnt vmcnt(7)
	v_lshlrev_b32_e32 v4, 16, v248
	v_and_b32_e32 v5, 0xffff0000, v248
	v_mul_f32_e32 v0, 0xbfb8aa3b, v4
	v_exp_f32_e32 v0, v0
	s_nop 0
	v_add_f32_e32 v0, 1.0, v0
	v_rcp_f32_e32 v6, v0
	v_mul_f32_e32 v0, 0xbfb8aa3b, v5
	v_exp_f32_e32 v0, v0
	s_nop 0
	v_add_f32_e32 v0, 1.0, v0
	v_rcp_f32_e32 v7, v0
	s_nop 0
	v_pk_mul_f32 v[4:5], v[6:7], v[4:5]
	s_nop 0
	v_pk_mul_f32 v[2:3], v[2:3], v[4:5]
	v_lshlrev_b32_e32 v4, 16, v249
	v_and_b32_e32 v5, 0xffff0000, v249
	v_mul_f32_e32 v1, 0xbfb8aa3b, v4
	v_exp_f32_e32 v1, v1
	v_cvt_pk_bf16_f32 v0, v2, v3
	v_pk_mul_f32 v[2:3], v[14:15], v[32:33] op_sel_hi:[1, 0]
	v_add_f32_e32 v1, 1.0, v1
	v_rcp_f32_e32 v6, v1
	v_mul_f32_e32 v1, 0xbfb8aa3b, v5
	v_exp_f32_e32 v1, v1
	s_nop 0
	v_add_f32_e32 v1, 1.0, v1
	v_rcp_f32_e32 v7, v1
	s_nop 0
	v_pk_mul_f32 v[4:5], v[6:7], v[4:5]
	s_nop 0
	v_pk_mul_f32 v[2:3], v[2:3], v[4:5]
	s_nop 0
	v_cvt_pk_bf16_f32 v1, v2, v3
	global_store_dwordx2 v[16:17], v[0:1], off offset:1136

; #define MFMA32(a, b, c) __builtin_amdgcn_mfma_f32_32x32x16_bf16((a), (b), (c), 0, 0, 0)
; DI float lo_bf(unsigned w) { return __uint_as_float(w << 16); }
; DI float hi_bf(unsigned w) { return __uint_as_float(w & 0xffff0000u); }
; DI float siluf_(float x) { return x * __builtin_amdgcn_rcpf(1.f + __builtin_amdgcn_exp2f(-1.4426950408889634f * x)); }
; DI float xsum32(float x) { auto r = __builtin_amdgcn_permlane32_swap(__float_as_uint(x), __float_as_uint(x), false, false); return __uint_as_float(r[0]) + __uint_as_float(r[1]); }
; template <int TYPE>
; DI void attn_item(const Params& p, int l, int bb, int head, int qb, char* smem) {
;     ...
; #pragma unroll
;         for (int kb = 0; kb < 2; kb++)
; #pragma unroll
;           for (int i = 0; i < 16; i++) { float e = __builtin_amdgcn_exp2f(s[kb][i]); s[kb][i] = e; psum += e; }
;       }
;       lrun[mp] += psum;
; #pragma unroll
;       for (int kb = 0; kb < 2; kb++)
; #pragma unroll
;         for (int s2 = 0; s2 < 2; s2++) {
;           unsigned pw[4];
; #pragma unroll
;           for (int e = 0; e < 4; e++) pw[e] = pack2(s[kb][8 * s2 + 2 * e], s[kb][8 * s2 + 2 * e + 1]);
;           u32x4 pu = u32x4{pw[0], pw[1], pw[2], pw[3]};
;           bf16x8 pf = __builtin_bit_cast(bf16x8, pu);
; #pragma unroll
;           for (int d = 0; d < 2; d++) {
;             const u16* vp = sV + (d * 32 + r) * 72 + kb * 32 + s2 * 16 + 4 * h;
;             s16x4 vlo = *(const s16x4*)vp, vhi = *(const s16x4*)(vp + 8);
;             bf16x8 vf = __builtin_shufflevector(vlo, vhi, 0, 1, 2, 3, 4, 5, 6, 7);
;             O[mp][d] = MFMA32(vf, pf, O[mp][d]);
;           }
;         }
;     }
;     __syncthreads();
;   }
;   float inv[NMAP];
; #pragma unroll
;   for (int mp = 0; mp < NMAP; mp++) { float lt = xsum32(lrun[mp]); inv[mp] = 1.f / lt; }
;     ...
; #pragma unroll
;   for (int d = 0; d < 2; d++)
; #pragma unroll
;     for (int g = 0; g < 4; g++) {
;       int dv0 = d * 32 + 8 * g + 4 * h2;
;       u32x2 gw = *(const u32x2*)(p.Gs + mh * 1024 + gcol + head * 64 + dv0);
;       float g0 = lo_bf(gw.x), g1 = hi_bf(gw.x), g2 = lo_bf(gw.y), g3 = hi_bf(gw.y);
;       u32x2 ow;
;       ow.x = pack2(val[d][4 * g] * siluf_(g0), val[d][4 * g + 1] * siluf_(g1));
;       ow.y = pack2(val[d][4 * g + 2] * siluf_(g2), val[d][4 * g + 3] * siluf_(g3));
;       *(u32x2*)(p.o + mh * DM + ocol + head * 64 + dv0) = ow;
;     }
.LBB0_406:
	v_exp_f32_e32 v90, v48
	v_exp_f32_e32 v91, v49
	v_exp_f32_e32 v92, v50
	v_exp_f32_e32 v93, v51
	v_add_f32_e32 v48, 0, v90
	v_exp_f32_e32 v94, v52
	v_add_f32_e32 v48, v48, v91
	v_exp_f32_e32 v95, v53
	v_add_f32_e32 v48, v92, v48
	v_exp_f32_e32 v96, v54
	v_add_f32_e32 v48, v93, v48
	v_exp_f32_e32 v97, v55
	v_add_f32_e32 v48, v94, v48
	v_exp_f32_e32 v98, v56
	v_add_f32_e32 v48, v95, v48
	v_exp_f32_e32 v99, v57
	v_add_f32_e32 v48, v96, v48
	v_exp_f32_e32 v100, v58
	v_add_f32_e32 v48, v97, v48
	v_add_f32_e32 v48, v98, v48
	v_add_f32_e32 v48, v99, v48
	v_add_f32_e32 v101, v100, v48
	v_exp_f32_e32 v102, v59
	ds_read2_b64 v[70:73], v80 offset0:128 offset1:130
	ds_read2_b64 v[74:77], v80 offset0:132 offset1:134
	ds_read2_b64 v[64:67], v81 offset0:128 offset1:130
	ds_read2_b64 v[56:59], v81 offset0:132 offset1:134
	ds_read2_b64 v[82:85], v80 offset0:136 offset1:138
	ds_read2_b64 v[52:55], v81 offset0:136 offset1:138
	ds_read2_b64 v[86:89], v80 offset0:140 offset1:142
	ds_read2_b64 v[48:51], v81 offset0:140 offset1:142
	s_waitcnt lgkmcnt(0)
	s_barrier
	v_mov_b32 v80, v198
	s_mul_i32 s26, s37, 0x1100
	v_ashrrev_i32_e32 v68, 1, v80
	v_and_b32_e32 v68, 0xffffffe0, v68
	v_add_u32_e32 v68, s38, v68
	v_and_or_b32 v68, v80, 31, v68
	v_ashrrev_i32_e32 v69, 31, v68
	v_lshl_add_u64 v[68:69], v[68:69], 0, s[26:27]
	v_lshlrev_b64 v[78:79], 11, v[68:69]
	v_lshl_add_u64 v[68:69], s[94:95], 0, v[78:79]
	s_lshl_b32 s26, s36, 7
	v_lshrrev_b32_e32 v80, 2, v80
	v_lshl_add_u64 v[68:69], v[68:69], 0, s[26:27]
	v_and_b32_e32 v176, 8, v80
	v_lshl_add_u64 v[68:69], v[68:69], 0, v[176:177]
	global_load_dwordx2 v[80:81], v[68:69], off
	global_load_dwordx2 v[236:237], v[68:69], off offset:16
	global_load_dwordx2 v[238:239], v[68:69], off offset:32
	global_load_dwordx2 v[240:241], v[68:69], off offset:48
	global_load_dwordx2 v[242:243], v[68:69], off offset:64
	global_load_dwordx2 v[244:245], v[68:69], off offset:80
	global_load_dwordx2 v[246:247], v[68:69], off offset:96
	global_load_dwordx2 v[248:249], v[68:69], off offset:112
	v_exp_f32_e32 v60, v60
	v_exp_f32_e32 v61, v61
	v_exp_f32_e32 v62, v62
	v_add_f32_e32 v101, v102, v101
	v_exp_f32_e32 v63, v63
	v_add_f32_e32 v101, v60, v101
	v_exp_f32_e32 v32, v32
	v_add_f32_e32 v101, v61, v101
	v_exp_f32_e32 v33, v33
	v_add_f32_e32 v101, v62, v101
	v_exp_f32_e32 v34, v34
	v_add_f32_e32 v101, v63, v101
	v_exp_f32_e32 v35, v35
	v_add_f32_e32 v101, v32, v101
	v_exp_f32_e32 v36, v36
	v_add_f32_e32 v101, v33, v101
	v_exp_f32_e32 v37, v37
	v_add_f32_e32 v101, v34, v101
	v_exp_f32_e32 v103, v38
	v_add_f32_e32 v101, v35, v101
	v_exp_f32_e32 v104, v39
	v_add_f32_e32 v101, v36, v101
	v_exp_f32_e32 v105, v40
	v_add_f32_e32 v38, v37, v101
	v_exp_f32_e32 v101, v41
	v_add_f32_e32 v38, v103, v38
	v_exp_f32_e32 v106, v42
	v_add_f32_e32 v38, v104, v38
	v_exp_f32_e32 v107, v43
	v_add_f32_e32 v38, v105, v38
	v_exp_f32_e32 v108, v44
	v_add_f32_e32 v38, v101, v38
	v_add_f32_e32 v38, v106, v38
	v_add_f32_e32 v38, v107, v38
	v_add_f32_e32 v109, v108, v38
	v_cvt_pk_bf16_f32 v38, v90, v91
	v_cvt_pk_bf16_f32 v39, v92, v93
	v_cvt_pk_bf16_f32 v40, v94, v95
	v_cvt_pk_bf16_f32 v41, v96, v97
	v_exp_f32_e32 v46, v46
	v_exp_f32_e32 v47, v47
	v_mfma_f32_32x32x16_bf16 v[16:31], v[70:73], v[38:41], v[16:31]
	v_exp_f32_e32 v70, v45
	v_cvt_pk_bf16_f32 v42, v98, v99
	v_cvt_pk_bf16_f32 v43, v100, v102
	v_cvt_pk_bf16_f32 v44, v60, v61
	v_cvt_pk_bf16_f32 v45, v62, v63
	v_add_f32_e32 v60, v70, v109
	v_add_f32_e32 v60, v46, v60
	v_mfma_f32_32x32x16_bf16 v[16:31], v[74:77], v[42:45], v[16:31]
	v_add_f32_e32 v71, v47, v60
	v_cvt_pk_bf16_f32 v61, v34, v35
	v_add_f32_e32 v34, v150, v71
	v_mov_b32_e32 v35, v34
	s_nop 1
	v_permlane32_swap_b32_e32 v34, v35
	v_cvt_pk_bf16_f32 v62, v36, v37
	v_add_f32_e32 v36, v34, v35
	v_cvt_pk_bf16_f32 v60, v32, v33
	v_cvt_pk_bf16_f32 v63, v103, v104
	v_div_scale_f32 v37, s[0:1], v36, v36, 1.0
	s_nop 0
	v_mfma_f32_32x32x16_bf16 v[16:31], v[82:85], v[60:63], v[16:31]
	v_rcp_f32_e32 v71, v37
	v_cvt_pk_bf16_f32 v35, v46, v47
	v_cvt_pk_bf16_f32 v32, v105, v101
	v_cvt_pk_bf16_f32 v33, v106, v107
	v_fma_f32 v46, -v37, v71, 1.0
	v_fmac_f32_e32 v71, v46, v71
	v_div_scale_f32 v46, vcc, 1.0, v36, 1.0
	v_mul_f32_e32 v47, v46, v71
	v_cvt_pk_bf16_f32 v34, v108, v70
	v_fma_f32 v70, -v37, v47, v46
	v_fmac_f32_e32 v47, v70, v71
	v_mfma_f32_32x32x16_bf16 v[16:31], v[86:89], v[32:35], v[16:31]
	v_fma_f32 v37, -v37, v47, v46
	v_div_fmas_f32 v37, v37, v71, v47
	v_div_fixup_f32 v36, v37, v36, 1.0
	s_waitcnt vmcnt(7)
	v_lshlrev_b32_e32 v46, 16, v80
	v_and_b32_e32 v47, 0xffff0000, v80
	v_mul_f32_e32 v37, 0xbfb8aa3b, v46
	v_exp_f32_e32 v37, v37
	v_mul_f32_e32 v70, 0xbfb8aa3b, v47
	v_exp_f32_e32 v71, v70
	v_lshlrev_b32_e32 v72, 16, v81
	s_nop 0
	v_pk_mul_f32 v[16:17], v[16:17], v[36:37] op_sel_hi:[1, 0]
	v_add_f32_e32 v37, 1.0, v37
	v_rcp_f32_e32 v70, v37
	v_add_f32_e32 v37, 1.0, v71
	v_rcp_f32_e32 v71, v37
	v_and_b32_e32 v73, 0xffff0000, v81
	v_mul_f32_e32 v37, 0xbfb8aa3b, v72
	v_exp_f32_e32 v37, v37
	v_mul_f32_e32 v74, 0xbfb8aa3b, v73
	v_exp_f32_e32 v74, v74
	v_pk_mul_f32 v[46:47], v[70:71], v[46:47]
	v_add_f32_e32 v37, 1.0, v37
	v_rcp_f32_e32 v70, v37
	v_add_f32_e32 v37, 1.0, v74
	v_rcp_f32_e32 v71, v37
	v_pk_mul_f32 v[16:17], v[16:17], v[46:47]
	v_readlane_b32 s36, v254, 18
	v_cvt_pk_bf16_f32 v46, v16, v17
	v_pk_mul_f32 v[16:17], v[18:19], v[36:37] op_sel_hi:[1, 0]
	v_pk_mul_f32 v[18:19], v[70:71], v[72:73]
	v_readlane_b32 s37, v254, 19
	v_pk_mul_f32 v[16:17], v[16:17], v[18:19]
	v_mfma_f32_32x32x16_bf16 v[0:15], v[64:67], v[38:41], v[0:15]
	v_cvt_pk_bf16_f32 v47, v16, v17
	v_lshl_add_u64 v[16:17], s[36:37], 0, v[78:79]
	v_lshl_add_u64 v[16:17], v[16:17], 0, s[26:27]
	v_lshl_add_u64 v[16:17], v[16:17], 0, v[176:177]
	global_store_dwordx2 v[16:17], v[46:47], off
	s_nop 0
	v_readlane_b32 s38, v254, 20
	v_mfma_f32_32x32x16_bf16 v[0:15], v[56:59], v[42:45], v[0:15]
	v_readlane_b32 s39, v254, 21
	s_waitcnt vmcnt(7)
; DI float lo_bf(unsigned w) { return __uint_as_float(w << 16); }
; DI float hi_bf(unsigned w) { return __uint_as_float(w & 0xffff0000u); }
; DI float siluf_(float x) { return x * __builtin_amdgcn_rcpf(1.f + __builtin_amdgcn_exp2f(-1.4426950408889634f * x)); }
; template <int TYPE>
; DI void attn_item(const Params& p, int l, int bb, int head, int qb, char* smem) {
;     ...
; #pragma unroll
;   for (int d = 0; d < 2; d++)
; #pragma unroll
;     for (int g = 0; g < 4; g++) {
;       int dv0 = d * 32 + 8 * g + 4 * h2;
;       u32x2 gw = *(const u32x2*)(p.Gs + mh * 1024 + gcol + head * 64 + dv0);
;       float g0 = lo_bf(gw.x), g1 = hi_bf(gw.x), g2 = lo_bf(gw.y), g3 = hi_bf(gw.y);
;       u32x2 ow;
;       ow.x = pack2(val[d][4 * g] * siluf_(g0), val[d][4 * g + 1] * siluf_(g1));
;       ow.y = pack2(val[d][4 * g + 2] * siluf_(g2), val[d][4 * g + 3] * siluf_(g3));
;       *(u32x2*)(p.o + mh * DM + ocol + head * 64 + dv0) = ow;
;     }
	v_lshlrev_b32_e32 v38, 16, v236
	v_and_b32_e32 v39, 0xffff0000, v236
	v_lshlrev_b32_e32 v18, 16, v237
	v_and_b32_e32 v19, 0xffff0000, v237
	v_mul_f32_e32 v37, 0xbfb8aa3b, v38
	v_mul_f32_e32 v40, 0xbfb8aa3b, v39
	v_mul_f32_e32 v41, 0xbfb8aa3b, v18
	v_mul_f32_e32 v46, 0xbfb8aa3b, v19
	v_exp_f32_e32 v37, v37
	v_exp_f32_e32 v40, v40
	v_exp_f32_e32 v41, v41
	v_exp_f32_e32 v46, v46
	v_add_f32_e32 v37, 1.0, v37
	v_add_f32_e32 v47, 1.0, v40
	v_add_f32_e32 v64, 1.0, v41
	v_add_f32_e32 v65, 1.0, v46
	v_rcp_f32_e32 v40, v37
	v_rcp_f32_e32 v41, v47
	v_rcp_f32_e32 v46, v64
	v_rcp_f32_e32 v47, v65
	v_pk_mul_f32 v[20:21], v[20:21], v[36:37] op_sel_hi:[1, 0]
	v_pk_mul_f32 v[22:23], v[22:23], v[36:37] op_sel_hi:[1, 0]
	v_pk_mul_f32 v[38:39], v[40:41], v[38:39]
	v_pk_mul_f32 v[18:19], v[46:47], v[18:19]
	v_pk_mul_f32 v[20:21], v[20:21], v[38:39]
	v_pk_mul_f32 v[18:19], v[22:23], v[18:19]
	v_cvt_pk_bf16_f32 v20, v20, v21
	v_cvt_pk_bf16_f32 v21, v18, v19
	global_store_dwordx2 v[16:17], v[20:21], off offset:16
	s_nop 0
	v_mfma_f32_32x32x16_bf16 v[0:15], v[52:55], v[60:63], v[0:15]
	s_waitcnt vmcnt(7)
	v_lshlrev_b32_e32 v20, 16, v238
	v_and_b32_e32 v21, 0xffff0000, v238
	v_lshlrev_b32_e32 v18, 16, v239
	v_and_b32_e32 v19, 0xffff0000, v239
	v_mul_f32_e32 v22, 0xbfb8aa3b, v20
	v_mul_f32_e32 v23, 0xbfb8aa3b, v21
	v_mul_f32_e32 v37, 0xbfb8aa3b, v18
	v_mul_f32_e32 v38, 0xbfb8aa3b, v19
	v_exp_f32_e32 v22, v22
	v_exp_f32_e32 v23, v23
	v_exp_f32_e32 v37, v37
	v_exp_f32_e32 v38, v38
	v_add_f32_e32 v22, 1.0, v22
	v_add_f32_e32 v23, 1.0, v23
	v_add_f32_e32 v37, 1.0, v37
	v_add_f32_e32 v39, 1.0, v38
	v_rcp_f32_e32 v22, v22
	v_rcp_f32_e32 v23, v23
	v_rcp_f32_e32 v38, v37
	v_rcp_f32_e32 v39, v39
	v_pk_mul_f32 v[24:25], v[24:25], v[36:37] op_sel_hi:[1, 0]
	v_pk_mul_f32 v[26:27], v[26:27], v[36:37] op_sel_hi:[1, 0]
	v_pk_mul_f32 v[20:21], v[22:23], v[20:21]
	v_pk_mul_f32 v[18:19], v[38:39], v[18:19]
	v_pk_mul_f32 v[20:21], v[24:25], v[20:21]
	v_pk_mul_f32 v[18:19], v[26:27], v[18:19]
	v_cvt_pk_bf16_f32 v20, v20, v21
	v_cvt_pk_bf16_f32 v21, v18, v19
	global_store_dwordx2 v[16:17], v[20:21], off offset:32
	s_nop 0
	v_pk_mul_f32 v[26:27], v[28:29], v[36:37] op_sel_hi:[1, 0]
	v_pk_mul_f32 v[28:29], v[30:31], v[36:37] op_sel_hi:[1, 0]
	v_mfma_f32_32x32x16_bf16 v[0:15], v[48:51], v[32:35], v[0:15]
	s_waitcnt vmcnt(7)
	v_lshlrev_b32_e32 v20, 16, v240
	v_and_b32_e32 v21, 0xffff0000, v240
	v_lshlrev_b32_e32 v18, 16, v241
	v_and_b32_e32 v19, 0xffff0000, v241
	v_mul_f32_e32 v22, 0xbfb8aa3b, v20
	v_mul_f32_e32 v23, 0xbfb8aa3b, v21
	v_mul_f32_e32 v24, 0xbfb8aa3b, v18
	v_mul_f32_e32 v25, 0xbfb8aa3b, v19
	v_exp_f32_e32 v22, v22
	v_exp_f32_e32 v23, v23
	v_exp_f32_e32 v24, v24
	v_exp_f32_e32 v25, v25
	v_add_f32_e32 v22, 1.0, v22
	v_add_f32_e32 v23, 1.0, v23
	v_add_f32_e32 v24, 1.0, v24
	v_add_f32_e32 v25, 1.0, v25
	v_rcp_f32_e32 v22, v22
	v_rcp_f32_e32 v23, v23
	v_rcp_f32_e32 v24, v24
	v_rcp_f32_e32 v25, v25
	v_pk_mul_f32 v[0:1], v[0:1], v[36:37] op_sel_hi:[1, 0]
	v_pk_mul_f32 v[20:21], v[22:23], v[20:21]
	v_pk_mul_f32 v[2:3], v[2:3], v[36:37] op_sel_hi:[1, 0]
	v_pk_mul_f32 v[18:19], v[24:25], v[18:19]
	v_pk_mul_f32 v[20:21], v[26:27], v[20:21]
	v_pk_mul_f32 v[18:19], v[28:29], v[18:19]
	v_cvt_pk_bf16_f32 v20, v20, v21
	v_cvt_pk_bf16_f32 v21, v18, v19
	global_store_dwordx2 v[16:17], v[20:21], off offset:48
	s_nop 0
	v_pk_mul_f32 v[4:5], v[4:5], v[36:37] op_sel_hi:[1, 0]
	v_pk_mul_f32 v[6:7], v[6:7], v[36:37] op_sel_hi:[1, 0]
	v_pk_mul_f32 v[8:9], v[8:9], v[36:37] op_sel_hi:[1, 0]
	v_pk_mul_f32 v[10:11], v[10:11], v[36:37] op_sel_hi:[1, 0]
	s_waitcnt vmcnt(7)
; DI float lo_bf(unsigned w) { return __uint_as_float(w << 16); }
; DI float hi_bf(unsigned w) { return __uint_as_float(w & 0xffff0000u); }
; DI float siluf_(float x) { return x * __builtin_amdgcn_rcpf(1.f + __builtin_amdgcn_exp2f(-1.4426950408889634f * x)); }
; template <int TYPE>
; DI void attn_item(const Params& p, int l, int bb, int head, int qb, char* smem) {
;     ...
; #pragma unroll
;   for (int d = 0; d < 2; d++)
; #pragma unroll
;     for (int g = 0; g < 4; g++) {
;       int dv0 = d * 32 + 8 * g + 4 * h2;
;       u32x2 gw = *(const u32x2*)(p.Gs + mh * 1024 + gcol + head * 64 + dv0);
;       float g0 = lo_bf(gw.x), g1 = hi_bf(gw.x), g2 = lo_bf(gw.y), g3 = hi_bf(gw.y);
;       u32x2 ow;
;       ow.x = pack2(val[d][4 * g] * siluf_(g0), val[d][4 * g + 1] * siluf_(g1));
;       ow.y = pack2(val[d][4 * g + 2] * siluf_(g2), val[d][4 * g + 3] * siluf_(g3));
;       *(u32x2*)(p.o + mh * DM + ocol + head * 64 + dv0) = ow;
;     }
	v_lshlrev_b32_e32 v20, 16, v242
	v_and_b32_e32 v21, 0xffff0000, v242
	v_lshlrev_b32_e32 v18, 16, v243
	v_and_b32_e32 v19, 0xffff0000, v243
	v_mul_f32_e32 v22, 0xbfb8aa3b, v20
	v_mul_f32_e32 v23, 0xbfb8aa3b, v21
	v_mul_f32_e32 v24, 0xbfb8aa3b, v18
	v_mul_f32_e32 v25, 0xbfb8aa3b, v19
	v_exp_f32_e32 v22, v22
	v_exp_f32_e32 v23, v23
	v_exp_f32_e32 v24, v24
	v_exp_f32_e32 v25, v25
	v_add_f32_e32 v22, 1.0, v22
	v_add_f32_e32 v23, 1.0, v23
	v_add_f32_e32 v24, 1.0, v24
	v_add_f32_e32 v25, 1.0, v25
	v_rcp_f32_e32 v22, v22
	v_rcp_f32_e32 v23, v23
	v_rcp_f32_e32 v24, v24
	v_rcp_f32_e32 v25, v25
	v_pk_mul_f32 v[20:21], v[22:23], v[20:21]
	s_nop 0
	v_pk_mul_f32 v[0:1], v[0:1], v[20:21]
	v_pk_mul_f32 v[18:19], v[24:25], v[18:19]
	v_cvt_pk_bf16_f32 v0, v0, v1
	v_pk_mul_f32 v[2:3], v[2:3], v[18:19]
	s_nop 0
	v_cvt_pk_bf16_f32 v1, v2, v3
	global_store_dwordx2 v[16:17], v[0:1], off offset:64
	s_nop 0
	s_waitcnt vmcnt(7)
	v_lshlrev_b32_e32 v2, 16, v244
	v_and_b32_e32 v3, 0xffff0000, v244
	v_lshlrev_b32_e32 v0, 16, v245
	v_and_b32_e32 v1, 0xffff0000, v245
	v_mul_f32_e32 v18, 0xbfb8aa3b, v2
	v_mul_f32_e32 v19, 0xbfb8aa3b, v3
	v_mul_f32_e32 v20, 0xbfb8aa3b, v0
	v_mul_f32_e32 v21, 0xbfb8aa3b, v1
	v_exp_f32_e32 v18, v18
	v_exp_f32_e32 v19, v19
	v_exp_f32_e32 v20, v20
	v_exp_f32_e32 v21, v21
	v_add_f32_e32 v18, 1.0, v18
	v_add_f32_e32 v19, 1.0, v19
	v_add_f32_e32 v20, 1.0, v20
	v_add_f32_e32 v21, 1.0, v21
	v_rcp_f32_e32 v18, v18
	v_rcp_f32_e32 v19, v19
	v_rcp_f32_e32 v20, v20
	v_rcp_f32_e32 v21, v21
	v_pk_mul_f32 v[2:3], v[18:19], v[2:3]
	s_nop 0
	v_pk_mul_f32 v[2:3], v[4:5], v[2:3]
	v_pk_mul_f32 v[0:1], v[20:21], v[0:1]
	v_cvt_pk_bf16_f32 v2, v2, v3
	v_pk_mul_f32 v[0:1], v[6:7], v[0:1]
	s_nop 0
	v_cvt_pk_bf16_f32 v3, v0, v1
	global_store_dwordx2 v[16:17], v[2:3], off offset:80
	s_nop 0
	s_waitcnt vmcnt(7)
	v_lshlrev_b32_e32 v2, 16, v246
	v_and_b32_e32 v3, 0xffff0000, v246
	v_lshlrev_b32_e32 v0, 16, v247
	v_and_b32_e32 v1, 0xffff0000, v247
	v_mul_f32_e32 v4, 0xbfb8aa3b, v2
	v_mul_f32_e32 v5, 0xbfb8aa3b, v3
	v_mul_f32_e32 v6, 0xbfb8aa3b, v0
	v_mul_f32_e32 v7, 0xbfb8aa3b, v1
	v_exp_f32_e32 v4, v4
	v_exp_f32_e32 v5, v5
	v_exp_f32_e32 v6, v6
	v_exp_f32_e32 v7, v7
	v_add_f32_e32 v4, 1.0, v4
	v_add_f32_e32 v5, 1.0, v5
	v_add_f32_e32 v6, 1.0, v6
	v_add_f32_e32 v7, 1.0, v7
	v_rcp_f32_e32 v4, v4
	v_rcp_f32_e32 v5, v5
	v_rcp_f32_e32 v6, v6
	v_rcp_f32_e32 v7, v7
	v_pk_mul_f32 v[2:3], v[4:5], v[2:3]
	s_nop 0
	v_pk_mul_f32 v[2:3], v[8:9], v[2:3]
	v_pk_mul_f32 v[0:1], v[6:7], v[0:1]
	v_cvt_pk_bf16_f32 v2, v2, v3
	v_pk_mul_f32 v[0:1], v[10:11], v[0:1]
	v_pk_mul_f32 v[8:9], v[12:13], v[36:37] op_sel_hi:[1, 0]
	v_cvt_pk_bf16_f32 v3, v0, v1
	global_store_dwordx2 v[16:17], v[2:3], off offset:96
	s_nop 0
	v_pk_mul_f32 v[10:11], v[14:15], v[36:37] op_sel_hi:[1, 0]
	s_waitcnt vmcnt(7)
	v_lshlrev_b32_e32 v2, 16, v248
	v_and_b32_e32 v3, 0xffff0000, v248
	v_lshlrev_b32_e32 v0, 16, v249
	v_and_b32_e32 v1, 0xffff0000, v249
	v_mul_f32_e32 v4, 0xbfb8aa3b, v2
	v_mul_f32_e32 v5, 0xbfb8aa3b, v3
	v_mul_f32_e32 v6, 0xbfb8aa3b, v0
	v_mul_f32_e32 v7, 0xbfb8aa3b, v1
	v_exp_f32_e32 v4, v4
	v_exp_f32_e32 v5, v5
	v_exp_f32_e32 v6, v6
	v_exp_f32_e32 v7, v7
	v_add_f32_e32 v4, 1.0, v4
	v_add_f32_e32 v5, 1.0, v5
	v_add_f32_e32 v6, 1.0, v6
	v_add_f32_e32 v7, 1.0, v7
	v_rcp_f32_e32 v4, v4
	v_rcp_f32_e32 v5, v5
	v_rcp_f32_e32 v6, v6
	v_rcp_f32_e32 v7, v7
	v_pk_mul_f32 v[2:3], v[4:5], v[2:3]
	s_nop 0
	v_pk_mul_f32 v[2:3], v[8:9], v[2:3]
	v_pk_mul_f32 v[0:1], v[6:7], v[0:1]
	v_cvt_pk_bf16_f32 v2, v2, v3
	v_pk_mul_f32 v[0:1], v[10:11], v[0:1]
	s_nop 0
	v_cvt_pk_bf16_f32 v3, v0, v1
	global_store_dwordx2 v[16:17], v[2:3], off offset:112
	s_cbranch_execnz .LBB0_156
	s_branch .LBB0_396

; DI void attn_prep_block(const Params& p, int l, int blk) {
;     ...
;   } else if (u < 20) {
;     int hd = u - 16;
;     const u16* s = prow + C_VD + hd * 64;
;     u16* d = p.VDt + (long)(bb * 4 + hd) * 64 * T + t;
; #pragma unroll
;     for (int q = 0; q < 8; q++) {
;       u32x4 w = *(const u32x4*)(s + q * 8);
;       unsigned ww[4] = {w.x, w.y, w.z, w.w};
; #pragma unroll
;       for (int e = 0; e < 4; e++) {
;         d[(long)(q * 8 + e * 2) * T] = (u16)(ww[e] & 0xffffu);
;         d[(long)(q * 8 + e * 2 + 1) * T] = (u16)(ww[e] >> 16);
;       }
;     }
.LBB0_424:
	s_andn2_saveexec_b64 s[52:53], s[62:63]
	s_cbranch_execz .LBB0_426
	s_waitcnt vmcnt(2)
	v_add_u32_e32 v6, -16, v90
	v_lshlrev_b32_e32 v176, 7, v6
	v_lshl_add_u64 v[4:5], v[0:1], 0, v[176:177]
	s_mov_b64 s[12:13], 0x1a00
	v_lshl_add_u64 v[2:3], v[4:5], 0, s[12:13]
	v_add_co_u32_e32 v4, vcc, 0x1000, v4
	v_lshl_add_u32 v0, v57, 2, v6
	s_nop 0
	v_addc_co_u32_e32 v5, vcc, 0, v5, vcc
	global_load_dwordx4 v[220:223], v[4:5], off offset:2560
	global_load_dwordx4 v[224:227], v[2:3], off offset:16
	global_load_dwordx4 v[228:231], v[2:3], off offset:32
	global_load_dwordx4 v[232:235], v[2:3], off offset:48
	global_load_dwordx4 v[236:239], v[2:3], off offset:64
	global_load_dwordx4 v[240:243], v[2:3], off offset:80
	global_load_dwordx4 v[244:247], v[2:3], off offset:96
	global_load_dwordx4 v[248:251], v[2:3], off offset:112
	v_mul_i32_i24_e32 v0, 0x88000, v0
	v_readlane_b32 s72, v252, 54
	v_ashrrev_i32_e32 v1, 31, v0
	v_readlane_b32 s86, v253, 4
	v_readlane_b32 s87, v253, 5
	v_mov_b32_e32 v57, v177
	s_movk_i32 s12, 0x4000
	v_lshl_add_u64 v[0:1], s[86:87], 0, v[0:1]
	v_lshl_add_u64 v[0:1], v[56:57], 1, v[0:1]
	s_waitcnt vmcnt(2)
	v_add_co_u32_e32 v8, vcc, s24, v0
	v_readlane_b32 s73, v252, 55
	s_nop 0
	v_addc_co_u32_e32 v9, vcc, 0, v1, vcc
	v_readlane_b32 s74, v252, 56
	v_readlane_b32 s75, v252, 57
	v_readlane_b32 s76, v252, 58
	v_readlane_b32 s77, v252, 59
	v_readlane_b32 s78, v252, 60
	v_readlane_b32 s79, v252, 61
	v_readlane_b32 s80, v252, 62
	v_readlane_b32 s81, v252, 63
	v_readlane_b32 s82, v253, 0
	v_readlane_b32 s83, v253, 1
	v_readlane_b32 s84, v253, 2
	v_readlane_b32 s85, v253, 3
	s_waitcnt vmcnt(7)
	global_store_short_d16_hi v[8:9], v220, off offset:512
	v_add_co_u32_e32 v8, vcc, s12, v0
	s_movk_i32 s12, 0x6000
	s_nop 0
	v_addc_co_u32_e32 v9, vcc, 0, v1, vcc
	global_store_short v[8:9], v221, off offset:1024
	v_add_co_u32_e32 v8, vcc, s12, v0
	s_mov_b32 s12, 0x8000
	s_nop 0
	v_addc_co_u32_e32 v9, vcc, 0, v1, vcc
	global_store_short v[0:1], v220, off
	v_add_co_u32_e32 v4, vcc, s12, v0
	global_store_short_d16_hi v[8:9], v221, off offset:1536
	s_nop 0
	v_addc_co_u32_e32 v5, vcc, 0, v1, vcc
	s_mov_b32 s12, 0xa000
	global_store_short v[4:5], v222, off offset:2048
	v_add_co_u32_e32 v4, vcc, s12, v0
	s_mov_b32 s12, 0xc000
	s_nop 0
	v_addc_co_u32_e32 v5, vcc, 0, v1, vcc
	global_store_short_d16_hi v[4:5], v222, off offset:2560
	v_add_co_u32_e32 v4, vcc, s12, v0
	s_mov_b32 s12, 0xe000
	s_nop 0
	v_addc_co_u32_e32 v5, vcc, 0, v1, vcc
	global_store_short v[4:5], v223, off offset:3072
	v_add_co_u32_e32 v4, vcc, s12, v0
	s_mov_b32 s12, 0x11000
	s_nop 0
	v_addc_co_u32_e32 v5, vcc, 0, v1, vcc
	global_store_short_d16_hi v[4:5], v223, off offset:3584
	s_nop 0
	v_add_co_u32_e32 v8, vcc, s12, v0
	s_mov_b32 s12, 0x13000
	s_nop 0
	v_addc_co_u32_e32 v9, vcc, 0, v1, vcc
	s_waitcnt vmcnt(14)
	global_store_short v[8:9], v224, off
	v_add_co_u32_e32 v8, vcc, s12, v0
	s_mov_b32 s12, 0x15000
	s_nop 0
	v_addc_co_u32_e32 v9, vcc, 0, v1, vcc
	global_store_short_d16_hi v[8:9], v224, off offset:512
	v_add_co_u32_e32 v8, vcc, s12, v0
	s_mov_b32 s12, 0x17000
	s_nop 0
	v_addc_co_u32_e32 v9, vcc, 0, v1, vcc
	global_store_short v[8:9], v225, off offset:1024
	v_add_co_u32_e32 v8, vcc, s12, v0
	s_mov_b32 s12, 0x19000
	s_nop 0
	v_addc_co_u32_e32 v9, vcc, 0, v1, vcc
	v_add_co_u32_e32 v4, vcc, s12, v0
	global_store_short_d16_hi v[8:9], v225, off offset:1536
	s_nop 0
	v_addc_co_u32_e32 v5, vcc, 0, v1, vcc
	s_mov_b32 s12, 0x1b000
	global_store_short v[4:5], v226, off offset:2048
	v_add_co_u32_e32 v4, vcc, s12, v0
	s_mov_b32 s12, 0x1d000
	s_nop 0
	v_addc_co_u32_e32 v5, vcc, 0, v1, vcc
	global_store_short_d16_hi v[4:5], v226, off offset:2560
	v_add_co_u32_e32 v4, vcc, s12, v0
	s_mov_b32 s12, 0x1f000
	s_nop 0
	v_addc_co_u32_e32 v5, vcc, 0, v1, vcc
	global_store_short v[4:5], v227, off offset:3072
	v_add_co_u32_e32 v4, vcc, s12, v0
	s_mov_b32 s12, 0x22000
	s_nop 0
	v_addc_co_u32_e32 v5, vcc, 0, v1, vcc
	global_store_short_d16_hi v[4:5], v227, off offset:3584
	s_nop 0
	v_add_co_u32_e32 v8, vcc, s12, v0
	s_mov_b32 s12, 0x24000
	s_nop 0
	v_addc_co_u32_e32 v9, vcc, 0, v1, vcc
	s_waitcnt vmcnt(21)
	global_store_short v[8:9], v228, off
	v_add_co_u32_e32 v8, vcc, s12, v0
	s_mov_b32 s12, 0x26000
	s_nop 0
	v_addc_co_u32_e32 v9, vcc, 0, v1, vcc
	global_store_short_d16_hi v[8:9], v228, off offset:512
	v_add_co_u32_e32 v8, vcc, s12, v0
	s_mov_b32 s12, 0x28000
	s_nop 0
	v_addc_co_u32_e32 v9, vcc, 0, v1, vcc
	global_store_short v[8:9], v229, off offset:1024
	v_add_co_u32_e32 v8, vcc, s12, v0
	s_mov_b32 s12, 0x2a000
	s_nop 0
	v_addc_co_u32_e32 v9, vcc, 0, v1, vcc
	v_add_co_u32_e32 v4, vcc, s12, v0
	global_store_short_d16_hi v[8:9], v229, off offset:1536
	s_nop 0
	v_addc_co_u32_e32 v5, vcc, 0, v1, vcc
	s_mov_b32 s12, 0x2c000
	global_store_short v[4:5], v230, off offset:2048
	v_add_co_u32_e32 v4, vcc, s12, v0
	s_mov_b32 s12, 0x2e000
	s_nop 0
	v_addc_co_u32_e32 v5, vcc, 0, v1, vcc
	global_store_short_d16_hi v[4:5], v230, off offset:2560
	v_add_co_u32_e32 v4, vcc, s12, v0
	s_mov_b32 s12, 0x33000
	s_nop 0
	v_addc_co_u32_e32 v5, vcc, 0, v1, vcc
	global_store_short v[4:5], v231, off offset:3072
	v_add_co_u32_e32 v4, vcc, s20, v0
	s_nop 1
	v_addc_co_u32_e32 v5, vcc, 0, v1, vcc
	global_store_short_d16_hi v[4:5], v231, off offset:3584
	s_nop 0
	v_add_co_u32_e32 v8, vcc, s12, v0
	s_mov_b32 s12, 0x35000
	s_nop 0
	v_addc_co_u32_e32 v9, vcc, 0, v1, vcc
	s_waitcnt vmcnt(28)
; DI void attn_prep_block(const Params& p, int l, int blk) {
;     ...
; #pragma unroll
;     for (int q = 0; q < 8; q++) {
;       u32x4 w = *(const u32x4*)(s + q * 8);
;       unsigned ww[4] = {w.x, w.y, w.z, w.w};
; #pragma unroll
;       for (int e = 0; e < 4; e++) {
;         d[(long)(q * 8 + e * 2) * T] = (u16)(ww[e] & 0xffffu);
;         d[(long)(q * 8 + e * 2 + 1) * T] = (u16)(ww[e] >> 16);
;       }
;     }
	global_store_short v[8:9], v232, off
	v_add_co_u32_e32 v8, vcc, s12, v0
	s_mov_b32 s12, 0x37000
	s_nop 0
	v_addc_co_u32_e32 v9, vcc, 0, v1, vcc
	global_store_short_d16_hi v[8:9], v232, off offset:512
	v_add_co_u32_e32 v8, vcc, s12, v0
	s_mov_b32 s12, 0x39000
	s_nop 0
	v_addc_co_u32_e32 v9, vcc, 0, v1, vcc
	global_store_short v[8:9], v233, off offset:1024
	v_add_co_u32_e32 v8, vcc, s12, v0
	s_mov_b32 s12, 0x3b000
	s_nop 0
	v_addc_co_u32_e32 v9, vcc, 0, v1, vcc
	v_add_co_u32_e32 v4, vcc, s12, v0
	global_store_short_d16_hi v[8:9], v233, off offset:1536
	s_nop 0
	v_addc_co_u32_e32 v5, vcc, 0, v1, vcc
	s_mov_b32 s12, 0x3d000
	global_store_short v[4:5], v234, off offset:2048
	v_add_co_u32_e32 v4, vcc, s12, v0
	s_mov_b32 s12, 0x3f000
	s_nop 0
	v_addc_co_u32_e32 v5, vcc, 0, v1, vcc
	global_store_short_d16_hi v[4:5], v234, off offset:2560
	v_add_co_u32_e32 v4, vcc, s12, v0
	s_mov_b32 s12, 0x41000
	s_nop 0
	v_addc_co_u32_e32 v5, vcc, 0, v1, vcc
	global_store_short v[4:5], v235, off offset:3072
	v_add_co_u32_e32 v4, vcc, s12, v0
	s_mov_b32 s12, 0x44000
	s_nop 0
	v_addc_co_u32_e32 v5, vcc, 0, v1, vcc
	global_store_short_d16_hi v[4:5], v235, off offset:3584
	s_nop 0
	v_add_co_u32_e32 v8, vcc, s12, v0
	s_mov_b32 s12, 0x46000
	s_nop 0
	v_addc_co_u32_e32 v9, vcc, 0, v1, vcc
	s_waitcnt vmcnt(35)
	global_store_short v[8:9], v236, off
	v_add_co_u32_e32 v8, vcc, s12, v0
	s_mov_b32 s12, 0x48000
	s_nop 0
	v_addc_co_u32_e32 v9, vcc, 0, v1, vcc
	global_store_short_d16_hi v[8:9], v236, off offset:512
	v_add_co_u32_e32 v8, vcc, s12, v0
	s_mov_b32 s12, 0x4a000
	s_nop 0
	v_addc_co_u32_e32 v9, vcc, 0, v1, vcc
	global_store_short v[8:9], v237, off offset:1024
	v_add_co_u32_e32 v8, vcc, s12, v0
	s_mov_b32 s12, 0x4c000
	s_nop 0
	v_addc_co_u32_e32 v9, vcc, 0, v1, vcc
	v_add_co_u32_e32 v4, vcc, s12, v0
	global_store_short_d16_hi v[8:9], v237, off offset:1536
	s_nop 0
	v_addc_co_u32_e32 v5, vcc, 0, v1, vcc
	s_mov_b32 s12, 0x4e000
	global_store_short v[4:5], v238, off offset:2048
	v_add_co_u32_e32 v4, vcc, s12, v0
	s_mov_b32 s12, 0x50000
	s_nop 0
	v_addc_co_u32_e32 v5, vcc, 0, v1, vcc
	global_store_short_d16_hi v[4:5], v238, off offset:2560
	v_add_co_u32_e32 v4, vcc, s12, v0
	s_mov_b32 s12, 0x52000
	s_nop 0
	v_addc_co_u32_e32 v5, vcc, 0, v1, vcc
	global_store_short v[4:5], v239, off offset:3072
	v_add_co_u32_e32 v4, vcc, s12, v0
	s_mov_b32 s12, 0x55000
	s_nop 0
	v_addc_co_u32_e32 v5, vcc, 0, v1, vcc
	global_store_short_d16_hi v[4:5], v239, off offset:3584
	s_nop 0
	v_add_co_u32_e32 v8, vcc, s12, v0
	s_mov_b32 s12, 0x57000
	s_nop 0
	v_addc_co_u32_e32 v9, vcc, 0, v1, vcc
	s_waitcnt vmcnt(42)
	global_store_short v[8:9], v240, off
	v_add_co_u32_e32 v8, vcc, s12, v0
	s_mov_b32 s12, 0x59000
	s_nop 0
	v_addc_co_u32_e32 v9, vcc, 0, v1, vcc
	global_store_short_d16_hi v[8:9], v240, off offset:512
	v_add_co_u32_e32 v8, vcc, s12, v0
	s_mov_b32 s12, 0x5b000
	s_nop 0
	v_addc_co_u32_e32 v9, vcc, 0, v1, vcc
	global_store_short v[8:9], v241, off offset:1024
	v_add_co_u32_e32 v8, vcc, s12, v0
	s_mov_b32 s12, 0x5d000
	s_nop 0
	v_addc_co_u32_e32 v9, vcc, 0, v1, vcc
	v_add_co_u32_e32 v4, vcc, s12, v0
	global_store_short_d16_hi v[8:9], v241, off offset:1536
	s_nop 0
	v_addc_co_u32_e32 v5, vcc, 0, v1, vcc
	s_mov_b32 s12, 0x5f000
	global_store_short v[4:5], v242, off offset:2048
	v_add_co_u32_e32 v4, vcc, s12, v0
	s_mov_b32 s12, 0x61000
	s_nop 0
	v_addc_co_u32_e32 v5, vcc, 0, v1, vcc
	global_store_short_d16_hi v[4:5], v242, off offset:2560
	v_add_co_u32_e32 v4, vcc, s12, v0
	s_mov_b32 s12, 0x63000
	s_nop 0
	v_addc_co_u32_e32 v5, vcc, 0, v1, vcc
	global_store_short v[4:5], v243, off offset:3072
	v_add_co_u32_e32 v4, vcc, s12, v0
	s_mov_b32 s12, 0x66000
	s_nop 0
	v_addc_co_u32_e32 v5, vcc, 0, v1, vcc
	global_store_short_d16_hi v[4:5], v243, off offset:3584
	s_nop 0
	v_add_co_u32_e32 v8, vcc, s12, v0
	s_mov_b32 s12, 0x68000
	s_nop 0
	v_addc_co_u32_e32 v9, vcc, 0, v1, vcc
	s_waitcnt vmcnt(49)
	global_store_short v[8:9], v244, off
	v_add_co_u32_e32 v8, vcc, s12, v0
	s_mov_b32 s12, 0x6a000
	s_nop 0
	v_addc_co_u32_e32 v9, vcc, 0, v1, vcc
	global_store_short_d16_hi v[8:9], v244, off offset:512
	v_add_co_u32_e32 v8, vcc, s12, v0
	s_mov_b32 s12, 0x6c000
	s_nop 0
	v_addc_co_u32_e32 v9, vcc, 0, v1, vcc
	global_store_short v[8:9], v245, off offset:1024
	v_add_co_u32_e32 v8, vcc, s12, v0
	s_mov_b32 s12, 0x6e000
	s_nop 0
	v_addc_co_u32_e32 v9, vcc, 0, v1, vcc
	v_add_co_u32_e32 v4, vcc, s12, v0
	global_store_short_d16_hi v[8:9], v245, off offset:1536
	s_nop 0
	v_addc_co_u32_e32 v5, vcc, 0, v1, vcc
	s_mov_b32 s12, 0x70000
	global_store_short v[4:5], v246, off offset:2048
	v_add_co_u32_e32 v4, vcc, s12, v0
	s_mov_b32 s12, 0x72000
	s_nop 0
	v_addc_co_u32_e32 v5, vcc, 0, v1, vcc
	global_store_short_d16_hi v[4:5], v246, off offset:2560
	v_add_co_u32_e32 v4, vcc, s12, v0
	s_mov_b32 s12, 0x74000
	s_nop 0
	v_addc_co_u32_e32 v5, vcc, 0, v1, vcc
	global_store_short v[4:5], v247, off offset:3072
	v_add_co_u32_e32 v4, vcc, s12, v0
	s_mov_b32 s12, 0x77000
	s_nop 0
	v_addc_co_u32_e32 v5, vcc, 0, v1, vcc
	global_store_short_d16_hi v[4:5], v247, off offset:3584
	s_nop 0
	v_add_co_u32_e32 v6, vcc, s12, v0
	s_mov_b32 s12, 0x79000
	s_nop 0
	v_addc_co_u32_e32 v7, vcc, 0, v1, vcc
	s_waitcnt vmcnt(56)
	global_store_short v[6:7], v248, off
	v_add_co_u32_e32 v6, vcc, s12, v0
	s_mov_b32 s12, 0x7b000
	s_nop 0
	v_addc_co_u32_e32 v7, vcc, 0, v1, vcc
	global_store_short_d16_hi v[6:7], v248, off offset:512
	v_add_co_u32_e32 v6, vcc, s12, v0
	s_mov_b32 s12, 0x7d000
	s_nop 0
	v_addc_co_u32_e32 v7, vcc, 0, v1, vcc
	global_store_short v[6:7], v249, off offset:1024
	v_add_co_u32_e32 v6, vcc, s12, v0
	s_mov_b32 s12, 0x7f000
	s_nop 0
	v_addc_co_u32_e32 v7, vcc, 0, v1, vcc
	v_add_co_u32_e32 v2, vcc, s12, v0
	global_store_short_d16_hi v[6:7], v249, off offset:1536
	s_nop 0
	v_addc_co_u32_e32 v3, vcc, 0, v1, vcc
	global_store_short v[2:3], v250, off offset:2048
	v_add_co_u32_e32 v2, vcc, 0x81000, v0
	s_nop 1
	v_addc_co_u32_e32 v3, vcc, 0, v1, vcc
	global_store_short_d16_hi v[2:3], v250, off offset:2560
	v_add_co_u32_e32 v2, vcc, 0x83000, v0
	s_nop 1
	v_addc_co_u32_e32 v3, vcc, 0, v1, vcc
	v_add_co_u32_e32 v0, vcc, 0x85000, v0
	global_store_short v[2:3], v251, off offset:3072
	s_nop 0
	v_addc_co_u32_e32 v1, vcc, 0, v1, vcc
	global_store_short_d16_hi v[0:1], v251, off offset:3584

; DI void attn_prep_block(const Params& p, int l, int blk) {
;     ...
;   } else if (u < 8) {
;     int hk = u - 6;
;     const u16* s = prow + C_VC + hk * 64;
;     u16* d = p.VCt + (long)(bb * 2 + hk) * 64 * T + t;
; #pragma unroll
;     for (int q = 0; q < 8; q++) {
;       u32x4 w = *(const u32x4*)(s + q * 8);
;       unsigned ww[4] = {w.x, w.y, w.z, w.w};
; #pragma unroll
;       for (int e = 0; e < 4; e++) {
;         d[(long)(q * 8 + e * 2) * T] = (u16)(ww[e] & 0xffffu);
;         d[(long)(q * 8 + e * 2 + 1) * T] = (u16)(ww[e] >> 16);
;       }
;     }
.LBB0_434:
	s_andn2_saveexec_b64 s[48:49], s[28:29]
	s_cbranch_execz .LBB0_436
	s_waitcnt vmcnt(2)
	v_add_u32_e32 v6, -6, v90
	v_lshlrev_b32_e32 v176, 7, v6
	v_lshl_add_u64 v[4:5], v[0:1], 0, v[176:177]
	s_mov_b64 s[12:13], 0x1300
	v_lshl_add_u64 v[2:3], v[4:5], 0, s[12:13]
	v_add_co_u32_e32 v4, vcc, 0x1000, v4
	v_lshl_add_u32 v0, v57, 1, v6
	s_nop 0
	v_addc_co_u32_e32 v5, vcc, 0, v5, vcc
	global_load_dwordx4 v[220:223], v[4:5], off offset:768
	global_load_dwordx4 v[224:227], v[2:3], off offset:16
	global_load_dwordx4 v[228:231], v[2:3], off offset:32
	global_load_dwordx4 v[232:235], v[2:3], off offset:48
	global_load_dwordx4 v[236:239], v[2:3], off offset:64
	global_load_dwordx4 v[240:243], v[2:3], off offset:80
	global_load_dwordx4 v[244:247], v[2:3], off offset:96
	global_load_dwordx4 v[248:251], v[2:3], off offset:112
	v_mul_i32_i24_e32 v0, 0x88000, v0
	v_readlane_b32 s52, v252, 54
	v_ashrrev_i32_e32 v1, 31, v0
	v_readlane_b32 s60, v252, 62
	v_readlane_b32 s61, v252, 63
	v_mov_b32_e32 v57, v177
	s_movk_i32 s12, 0x4000
	v_lshl_add_u64 v[0:1], s[60:61], 0, v[0:1]
	v_lshl_add_u64 v[0:1], v[56:57], 1, v[0:1]
	s_waitcnt vmcnt(2)
	v_add_co_u32_e32 v8, vcc, s24, v0
	v_readlane_b32 s53, v252, 55
	s_nop 0
	v_addc_co_u32_e32 v9, vcc, 0, v1, vcc
	v_readlane_b32 s54, v252, 56
	v_readlane_b32 s55, v252, 57
	v_readlane_b32 s56, v252, 58
	v_readlane_b32 s57, v252, 59
	v_readlane_b32 s58, v252, 60
	v_readlane_b32 s59, v252, 61
	v_readlane_b32 s62, v253, 0
	v_readlane_b32 s63, v253, 1
	v_readlane_b32 s64, v253, 2
	v_readlane_b32 s65, v253, 3
	v_readlane_b32 s66, v253, 4
	v_readlane_b32 s67, v253, 5
	s_waitcnt vmcnt(7)
	global_store_short_d16_hi v[8:9], v220, off offset:512
	v_add_co_u32_e32 v8, vcc, s12, v0
	s_movk_i32 s12, 0x6000
	s_nop 0
	v_addc_co_u32_e32 v9, vcc, 0, v1, vcc
	global_store_short v[8:9], v221, off offset:1024
	v_add_co_u32_e32 v8, vcc, s12, v0
	s_mov_b32 s12, 0x8000
	s_nop 0
	v_addc_co_u32_e32 v9, vcc, 0, v1, vcc
	global_store_short v[0:1], v220, off
	v_add_co_u32_e32 v4, vcc, s12, v0
	global_store_short_d16_hi v[8:9], v221, off offset:1536
	s_nop 0
	v_addc_co_u32_e32 v5, vcc, 0, v1, vcc
	s_mov_b32 s12, 0xa000
	global_store_short v[4:5], v222, off offset:2048
	v_add_co_u32_e32 v4, vcc, s12, v0
	s_mov_b32 s12, 0xc000
	s_nop 0
	v_addc_co_u32_e32 v5, vcc, 0, v1, vcc
	global_store_short_d16_hi v[4:5], v222, off offset:2560
	v_add_co_u32_e32 v4, vcc, s12, v0
	s_mov_b32 s12, 0xe000
	s_nop 0
	v_addc_co_u32_e32 v5, vcc, 0, v1, vcc
	global_store_short v[4:5], v223, off offset:3072
	v_add_co_u32_e32 v4, vcc, s12, v0
	s_mov_b32 s12, 0x11000
	s_nop 0
	v_addc_co_u32_e32 v5, vcc, 0, v1, vcc
	global_store_short_d16_hi v[4:5], v223, off offset:3584
	s_nop 0
	v_add_co_u32_e32 v8, vcc, s12, v0
	s_mov_b32 s12, 0x13000
	s_nop 0
	v_addc_co_u32_e32 v9, vcc, 0, v1, vcc
	s_waitcnt vmcnt(14)
	global_store_short v[8:9], v224, off
	v_add_co_u32_e32 v8, vcc, s12, v0
	s_mov_b32 s12, 0x15000
	s_nop 0
	v_addc_co_u32_e32 v9, vcc, 0, v1, vcc
	global_store_short_d16_hi v[8:9], v224, off offset:512
	v_add_co_u32_e32 v8, vcc, s12, v0
	s_mov_b32 s12, 0x17000
	s_nop 0
	v_addc_co_u32_e32 v9, vcc, 0, v1, vcc
	global_store_short v[8:9], v225, off offset:1024
	v_add_co_u32_e32 v8, vcc, s12, v0
	s_mov_b32 s12, 0x19000
	s_nop 0
	v_addc_co_u32_e32 v9, vcc, 0, v1, vcc
	v_add_co_u32_e32 v4, vcc, s12, v0
	global_store_short_d16_hi v[8:9], v225, off offset:1536
	s_nop 0
	v_addc_co_u32_e32 v5, vcc, 0, v1, vcc
	s_mov_b32 s12, 0x1b000
	global_store_short v[4:5], v226, off offset:2048
	v_add_co_u32_e32 v4, vcc, s12, v0
	s_mov_b32 s12, 0x1d000
	s_nop 0
	v_addc_co_u32_e32 v5, vcc, 0, v1, vcc
	global_store_short_d16_hi v[4:5], v226, off offset:2560
	v_add_co_u32_e32 v4, vcc, s12, v0
	s_mov_b32 s12, 0x1f000
	s_nop 0
	v_addc_co_u32_e32 v5, vcc, 0, v1, vcc
	global_store_short v[4:5], v227, off offset:3072
	v_add_co_u32_e32 v4, vcc, s12, v0
	s_mov_b32 s12, 0x22000
	s_nop 0
	v_addc_co_u32_e32 v5, vcc, 0, v1, vcc
	global_store_short_d16_hi v[4:5], v227, off offset:3584
	s_nop 0
	v_add_co_u32_e32 v8, vcc, s12, v0
	s_mov_b32 s12, 0x24000
	s_nop 0
	v_addc_co_u32_e32 v9, vcc, 0, v1, vcc
	s_waitcnt vmcnt(21)
	global_store_short v[8:9], v228, off
	v_add_co_u32_e32 v8, vcc, s12, v0
	s_mov_b32 s12, 0x26000
	s_nop 0
	v_addc_co_u32_e32 v9, vcc, 0, v1, vcc
	global_store_short_d16_hi v[8:9], v228, off offset:512
	v_add_co_u32_e32 v8, vcc, s12, v0
	s_mov_b32 s12, 0x28000
	s_nop 0
	v_addc_co_u32_e32 v9, vcc, 0, v1, vcc
	global_store_short v[8:9], v229, off offset:1024
	v_add_co_u32_e32 v8, vcc, s12, v0
	s_mov_b32 s12, 0x2a000
	s_nop 0
	v_addc_co_u32_e32 v9, vcc, 0, v1, vcc
	v_add_co_u32_e32 v4, vcc, s12, v0
	global_store_short_d16_hi v[8:9], v229, off offset:1536
	s_nop 0
	v_addc_co_u32_e32 v5, vcc, 0, v1, vcc
	s_mov_b32 s12, 0x2c000
	global_store_short v[4:5], v230, off offset:2048
	v_add_co_u32_e32 v4, vcc, s12, v0
	s_mov_b32 s12, 0x2e000
	s_nop 0
	v_addc_co_u32_e32 v5, vcc, 0, v1, vcc
	global_store_short_d16_hi v[4:5], v230, off offset:2560
	v_add_co_u32_e32 v4, vcc, s12, v0
	s_mov_b32 s12, 0x33000
	s_nop 0
	v_addc_co_u32_e32 v5, vcc, 0, v1, vcc
	global_store_short v[4:5], v231, off offset:3072
	v_add_co_u32_e32 v4, vcc, s20, v0
	s_nop 1
	v_addc_co_u32_e32 v5, vcc, 0, v1, vcc
	global_store_short_d16_hi v[4:5], v231, off offset:3584
	s_nop 0
	v_add_co_u32_e32 v8, vcc, s12, v0
	s_mov_b32 s12, 0x35000
	s_nop 0
	v_addc_co_u32_e32 v9, vcc, 0, v1, vcc
	s_waitcnt vmcnt(28)
; DI void attn_prep_block(const Params& p, int l, int blk) {
;     ...
; #pragma unroll
;     for (int q = 0; q < 8; q++) {
;       u32x4 w = *(const u32x4*)(s + q * 8);
;       unsigned ww[4] = {w.x, w.y, w.z, w.w};
; #pragma unroll
;       for (int e = 0; e < 4; e++) {
;         d[(long)(q * 8 + e * 2) * T] = (u16)(ww[e] & 0xffffu);
;         d[(long)(q * 8 + e * 2 + 1) * T] = (u16)(ww[e] >> 16);
;       }
;     }
	global_store_short v[8:9], v232, off
	v_add_co_u32_e32 v8, vcc, s12, v0
	s_mov_b32 s12, 0x37000
	s_nop 0
	v_addc_co_u32_e32 v9, vcc, 0, v1, vcc
	global_store_short_d16_hi v[8:9], v232, off offset:512
	v_add_co_u32_e32 v8, vcc, s12, v0
	s_mov_b32 s12, 0x39000
	s_nop 0
	v_addc_co_u32_e32 v9, vcc, 0, v1, vcc
	global_store_short v[8:9], v233, off offset:1024
	v_add_co_u32_e32 v8, vcc, s12, v0
	s_mov_b32 s12, 0x3b000
	s_nop 0
	v_addc_co_u32_e32 v9, vcc, 0, v1, vcc
	v_add_co_u32_e32 v4, vcc, s12, v0
	global_store_short_d16_hi v[8:9], v233, off offset:1536
	s_nop 0
	v_addc_co_u32_e32 v5, vcc, 0, v1, vcc
	s_mov_b32 s12, 0x3d000
	global_store_short v[4:5], v234, off offset:2048
	v_add_co_u32_e32 v4, vcc, s12, v0
	s_mov_b32 s12, 0x3f000
	s_nop 0
	v_addc_co_u32_e32 v5, vcc, 0, v1, vcc
	global_store_short_d16_hi v[4:5], v234, off offset:2560
	v_add_co_u32_e32 v4, vcc, s12, v0
	s_mov_b32 s12, 0x41000
	s_nop 0
	v_addc_co_u32_e32 v5, vcc, 0, v1, vcc
	global_store_short v[4:5], v235, off offset:3072
	v_add_co_u32_e32 v4, vcc, s12, v0
	s_mov_b32 s12, 0x44000
	s_nop 0
	v_addc_co_u32_e32 v5, vcc, 0, v1, vcc
	global_store_short_d16_hi v[4:5], v235, off offset:3584
	s_nop 0
	v_add_co_u32_e32 v8, vcc, s12, v0
	s_mov_b32 s12, 0x46000
	s_nop 0
	v_addc_co_u32_e32 v9, vcc, 0, v1, vcc
	s_waitcnt vmcnt(35)
	global_store_short v[8:9], v236, off
	v_add_co_u32_e32 v8, vcc, s12, v0
	s_mov_b32 s12, 0x48000
	s_nop 0
	v_addc_co_u32_e32 v9, vcc, 0, v1, vcc
	global_store_short_d16_hi v[8:9], v236, off offset:512
	v_add_co_u32_e32 v8, vcc, s12, v0
	s_mov_b32 s12, 0x4a000
	s_nop 0
	v_addc_co_u32_e32 v9, vcc, 0, v1, vcc
	global_store_short v[8:9], v237, off offset:1024
	v_add_co_u32_e32 v8, vcc, s12, v0
	s_mov_b32 s12, 0x4c000
	s_nop 0
	v_addc_co_u32_e32 v9, vcc, 0, v1, vcc
	v_add_co_u32_e32 v4, vcc, s12, v0
	global_store_short_d16_hi v[8:9], v237, off offset:1536
	s_nop 0
	v_addc_co_u32_e32 v5, vcc, 0, v1, vcc
	s_mov_b32 s12, 0x4e000
	global_store_short v[4:5], v238, off offset:2048
	v_add_co_u32_e32 v4, vcc, s12, v0
	s_mov_b32 s12, 0x50000
	s_nop 0
	v_addc_co_u32_e32 v5, vcc, 0, v1, vcc
	global_store_short_d16_hi v[4:5], v238, off offset:2560
	v_add_co_u32_e32 v4, vcc, s12, v0
	s_mov_b32 s12, 0x52000
	s_nop 0
	v_addc_co_u32_e32 v5, vcc, 0, v1, vcc
	global_store_short v[4:5], v239, off offset:3072
	v_add_co_u32_e32 v4, vcc, s12, v0
	s_mov_b32 s12, 0x55000
	s_nop 0
	v_addc_co_u32_e32 v5, vcc, 0, v1, vcc
	global_store_short_d16_hi v[4:5], v239, off offset:3584
	s_nop 0
	v_add_co_u32_e32 v8, vcc, s12, v0
	s_mov_b32 s12, 0x57000
	s_nop 0
	v_addc_co_u32_e32 v9, vcc, 0, v1, vcc
	s_waitcnt vmcnt(42)
	global_store_short v[8:9], v240, off
	v_add_co_u32_e32 v8, vcc, s12, v0
	s_mov_b32 s12, 0x59000
	s_nop 0
	v_addc_co_u32_e32 v9, vcc, 0, v1, vcc
	global_store_short_d16_hi v[8:9], v240, off offset:512
	v_add_co_u32_e32 v8, vcc, s12, v0
	s_mov_b32 s12, 0x5b000
	s_nop 0
	v_addc_co_u32_e32 v9, vcc, 0, v1, vcc
	global_store_short v[8:9], v241, off offset:1024
	v_add_co_u32_e32 v8, vcc, s12, v0
	s_mov_b32 s12, 0x5d000
	s_nop 0
	v_addc_co_u32_e32 v9, vcc, 0, v1, vcc
	v_add_co_u32_e32 v4, vcc, s12, v0
	global_store_short_d16_hi v[8:9], v241, off offset:1536
	s_nop 0
	v_addc_co_u32_e32 v5, vcc, 0, v1, vcc
	s_mov_b32 s12, 0x5f000
	global_store_short v[4:5], v242, off offset:2048
	v_add_co_u32_e32 v4, vcc, s12, v0
	s_mov_b32 s12, 0x61000
	s_nop 0
	v_addc_co_u32_e32 v5, vcc, 0, v1, vcc
	global_store_short_d16_hi v[4:5], v242, off offset:2560
	v_add_co_u32_e32 v4, vcc, s12, v0
	s_mov_b32 s12, 0x63000
	s_nop 0
	v_addc_co_u32_e32 v5, vcc, 0, v1, vcc
	global_store_short v[4:5], v243, off offset:3072
	v_add_co_u32_e32 v4, vcc, s12, v0
	s_mov_b32 s12, 0x66000
	s_nop 0
	v_addc_co_u32_e32 v5, vcc, 0, v1, vcc
	global_store_short_d16_hi v[4:5], v243, off offset:3584
	s_nop 0
	v_add_co_u32_e32 v8, vcc, s12, v0
	s_mov_b32 s12, 0x68000
	s_nop 0
	v_addc_co_u32_e32 v9, vcc, 0, v1, vcc
	s_waitcnt vmcnt(49)
	global_store_short v[8:9], v244, off
	v_add_co_u32_e32 v8, vcc, s12, v0
	s_mov_b32 s12, 0x6a000
	s_nop 0
	v_addc_co_u32_e32 v9, vcc, 0, v1, vcc
	global_store_short_d16_hi v[8:9], v244, off offset:512
	v_add_co_u32_e32 v8, vcc, s12, v0
	s_mov_b32 s12, 0x6c000
	s_nop 0
	v_addc_co_u32_e32 v9, vcc, 0, v1, vcc
	global_store_short v[8:9], v245, off offset:1024
	v_add_co_u32_e32 v8, vcc, s12, v0
	s_mov_b32 s12, 0x6e000
	s_nop 0
	v_addc_co_u32_e32 v9, vcc, 0, v1, vcc
	v_add_co_u32_e32 v4, vcc, s12, v0
	global_store_short_d16_hi v[8:9], v245, off offset:1536
	s_nop 0
	v_addc_co_u32_e32 v5, vcc, 0, v1, vcc
	s_mov_b32 s12, 0x70000
	global_store_short v[4:5], v246, off offset:2048
	v_add_co_u32_e32 v4, vcc, s12, v0
	s_mov_b32 s12, 0x72000
	s_nop 0
	v_addc_co_u32_e32 v5, vcc, 0, v1, vcc
	global_store_short_d16_hi v[4:5], v246, off offset:2560
	v_add_co_u32_e32 v4, vcc, s12, v0
	s_mov_b32 s12, 0x74000
	s_nop 0
	v_addc_co_u32_e32 v5, vcc, 0, v1, vcc
	global_store_short v[4:5], v247, off offset:3072
	v_add_co_u32_e32 v4, vcc, s12, v0
	s_mov_b32 s12, 0x77000
	s_nop 0
	v_addc_co_u32_e32 v5, vcc, 0, v1, vcc
	global_store_short_d16_hi v[4:5], v247, off offset:3584
	s_nop 0
	v_add_co_u32_e32 v6, vcc, s12, v0
	s_mov_b32 s12, 0x79000
	s_nop 0
	v_addc_co_u32_e32 v7, vcc, 0, v1, vcc
	s_waitcnt vmcnt(56)
	global_store_short v[6:7], v248, off
	v_add_co_u32_e32 v6, vcc, s12, v0
	s_mov_b32 s12, 0x7b000
	s_nop 0
	v_addc_co_u32_e32 v7, vcc, 0, v1, vcc
	global_store_short_d16_hi v[6:7], v248, off offset:512
	v_add_co_u32_e32 v6, vcc, s12, v0
	s_mov_b32 s12, 0x7d000
	s_nop 0
	v_addc_co_u32_e32 v7, vcc, 0, v1, vcc
	global_store_short v[6:7], v249, off offset:1024
	v_add_co_u32_e32 v6, vcc, s12, v0
	s_mov_b32 s12, 0x7f000
	s_nop 0
	v_addc_co_u32_e32 v7, vcc, 0, v1, vcc
	v_add_co_u32_e32 v2, vcc, s12, v0
	global_store_short_d16_hi v[6:7], v249, off offset:1536
	s_nop 0
	v_addc_co_u32_e32 v3, vcc, 0, v1, vcc
	global_store_short v[2:3], v250, off offset:2048
	v_add_co_u32_e32 v2, vcc, 0x81000, v0
	s_nop 1
	v_addc_co_u32_e32 v3, vcc, 0, v1, vcc
	global_store_short_d16_hi v[2:3], v250, off offset:2560
	v_add_co_u32_e32 v2, vcc, 0x83000, v0
	s_nop 1
	v_addc_co_u32_e32 v3, vcc, 0, v1, vcc
	v_add_co_u32_e32 v0, vcc, 0x85000, v0
	global_store_short v[2:3], v251, off offset:3072
	s_nop 0
	v_addc_co_u32_e32 v1, vcc, 0, v1, vcc
	global_store_short_d16_hi v[0:1], v251, off offset:3584
